# back-edge rotation (guide 7.11) in the five 8-phase GEMM K-loops: scalar loop-carried updates and next-iteration set-up moved in front of the loop-back barrier
# baseline (speedup 1.0000x reference)
.Lrot_0:
	v_add_u32_e32 v162, s65, v160
	v_add_u32_e32 v178, s61, v160
	ds_read_b128 v[148:151], v162
	ds_read_b128 v[152:155], v162 offset:1024
	ds_read_b128 v[156:159], v162 offset:2048
	ds_read_b128 v[162:165], v162 offset:3072
	ds_read_b128 v[166:169], v178
	ds_read_b128 v[170:173], v178 offset:1024
	ds_read_b128 v[174:177], v178 offset:2048
	ds_read_b128 v[178:181], v178 offset:3072
	v_lshl_add_u64 v[214:215], s[6:7], 0, v[144:145]
	s_add_i32 m0, s85, 0xc000
	ds_read_b128 v[182:185], v161
	ds_read_b128 v[186:189], v161 offset:1024
	ds_read_b128 v[190:193], v161 offset:2048
	ds_read_b128 v[194:197], v161 offset:3072
	ds_read_b128 v[198:201], v161 offset:4096
	ds_read_b128 v[202:205], v161 offset:5120
	ds_read_b128 v[206:209], v161 offset:6144
	ds_read_b128 v[210:213], v161 offset:7168
	global_load_lds_dwordx4 v[214:215], off
	v_lshl_add_u64 v[214:215], s[6:7], 0, v[146:147]
	s_add_i32 m0, s85, 0xe000
	s_nop 0
	global_load_lds_dwordx4 v[214:215], off
	s_waitcnt vmcnt(8)
	s_waitcnt lgkmcnt(0)
	s_barrier
	s_setprio 1
	s_waitcnt lgkmcnt(0)
	v_mfma_f32_16x16x32_bf16 v[122:125], v[148:151], v[182:185], v[122:125]
	v_mfma_f32_16x16x32_bf16 v[126:129], v[156:159], v[182:185], v[126:129]
	v_mfma_f32_16x16x32_bf16 v[118:121], v[148:151], v[190:193], v[118:121]
	v_mfma_f32_16x16x32_bf16 v[114:117], v[156:159], v[190:193], v[114:117]
	v_mfma_f32_16x16x32_bf16 v[110:113], v[148:151], v[198:201], v[110:113]
	v_mfma_f32_16x16x32_bf16 v[106:109], v[156:159], v[198:201], v[106:109]
	v_mfma_f32_16x16x32_bf16 v[102:105], v[148:151], v[206:209], v[102:105]
	v_mfma_f32_16x16x32_bf16 v[98:101], v[156:159], v[206:209], v[98:101]
	v_mfma_f32_16x16x32_bf16 v[122:125], v[152:155], v[186:189], v[122:125]
	v_mfma_f32_16x16x32_bf16 v[126:129], v[162:165], v[186:189], v[126:129]
	v_mfma_f32_16x16x32_bf16 v[118:121], v[152:155], v[194:197], v[118:121]
	v_mfma_f32_16x16x32_bf16 v[114:117], v[162:165], v[194:197], v[114:117]
	v_mfma_f32_16x16x32_bf16 v[110:113], v[152:155], v[202:205], v[110:113]
	v_mfma_f32_16x16x32_bf16 v[106:109], v[162:165], v[202:205], v[106:109]
	v_mfma_f32_16x16x32_bf16 v[102:105], v[152:155], v[210:213], v[102:105]
	v_mfma_f32_16x16x32_bf16 v[98:101], v[162:165], v[210:213], v[98:101]
	s_setprio 0
	s_setprio 1
	v_mfma_f32_16x16x32_bf16 v[62:65], v[166:169], v[182:185], v[62:65]
	v_mfma_f32_16x16x32_bf16 v[58:61], v[174:177], v[182:185], v[58:61]
	v_mfma_f32_16x16x32_bf16 v[54:57], v[166:169], v[190:193], v[54:57]
	v_mfma_f32_16x16x32_bf16 v[50:53], v[174:177], v[190:193], v[50:53]
	v_mfma_f32_16x16x32_bf16 v[46:49], v[166:169], v[198:201], v[46:49]
	v_mfma_f32_16x16x32_bf16 v[42:45], v[174:177], v[198:201], v[42:45]
	v_mfma_f32_16x16x32_bf16 v[38:41], v[166:169], v[206:209], v[38:41]
	v_mfma_f32_16x16x32_bf16 v[34:37], v[174:177], v[206:209], v[34:37]
	v_mfma_f32_16x16x32_bf16 v[62:65], v[170:173], v[186:189], v[62:65]
	v_mfma_f32_16x16x32_bf16 v[58:61], v[178:181], v[186:189], v[58:61]
	v_mfma_f32_16x16x32_bf16 v[54:57], v[170:173], v[194:197], v[54:57]
	v_mfma_f32_16x16x32_bf16 v[50:53], v[178:181], v[194:197], v[50:53]
	v_mfma_f32_16x16x32_bf16 v[46:49], v[170:173], v[202:205], v[46:49]
	v_mfma_f32_16x16x32_bf16 v[42:45], v[178:181], v[202:205], v[42:45]
	v_mfma_f32_16x16x32_bf16 v[38:41], v[170:173], v[210:213], v[38:41]
	v_mfma_f32_16x16x32_bf16 v[34:37], v[178:181], v[210:213], v[34:37]
	s_setprio 0
	s_barrier
	s_add_i32 s65, s65, s84
	v_lshl_add_u64 v[214:215], s[8:9], 0, v[134:135]
	s_mov_b32 m0, s65
	ds_read_b128 v[182:185], v161 offset:16384
	ds_read_b128 v[186:189], v161 offset:17408
	ds_read_b128 v[190:193], v161 offset:18432
	ds_read_b128 v[194:197], v161 offset:19456
	ds_read_b128 v[198:201], v161 offset:20480
	ds_read_b128 v[202:205], v161 offset:21504
	ds_read_b128 v[206:209], v161 offset:22528
	ds_read_b128 v[210:213], v161 offset:23552
	global_load_lds_dwordx4 v[214:215], off
	s_add_i32 m0, s65, 0x2000
	s_add_u32 s76, s8, 0x40000
	v_lshl_add_u64 v[216:217], s[8:9], 0, v[130:131]
	s_addc_u32 s77, s9, 0
	s_add_i32 s61, s61, s84
	global_load_lds_dwordx4 v[216:217], off
	v_lshl_add_u64 v[218:219], s[76:77], 0, v[134:135]
	s_mov_b32 m0, s61
	v_lshl_add_u64 v[220:221], s[74:75], 0, v[132:133]
	global_load_lds_dwordx4 v[218:219], off
	v_lshl_add_u64 v[218:219], s[76:77], 0, v[130:131]
	s_add_i32 m0, s61, 0x2000
	s_nop 0
	global_load_lds_dwordx4 v[218:219], off
	v_lshl_add_u64 v[218:219], s[74:75], 0, v[136:137]
	s_mov_b32 m0, s85
	s_nop 0
	global_load_lds_dwordx4 v[218:219], off
	s_mov_b32 m0, s86
	s_nop 0
	global_load_lds_dwordx4 v[220:221], off
	s_waitcnt vmcnt(8)
	s_waitcnt lgkmcnt(0)
	s_barrier
	s_setprio 1
	s_waitcnt lgkmcnt(0)
	v_mfma_f32_16x16x32_bf16 v[94:97], v[148:151], v[182:185], v[94:97]
	v_mfma_f32_16x16x32_bf16 v[90:93], v[156:159], v[182:185], v[90:93]
	v_mfma_f32_16x16x32_bf16 v[86:89], v[148:151], v[190:193], v[86:89]
	v_mfma_f32_16x16x32_bf16 v[82:85], v[156:159], v[190:193], v[82:85]
	v_mfma_f32_16x16x32_bf16 v[78:81], v[148:151], v[198:201], v[78:81]
	v_mfma_f32_16x16x32_bf16 v[74:77], v[156:159], v[198:201], v[74:77]
	v_mfma_f32_16x16x32_bf16 v[70:73], v[148:151], v[206:209], v[70:73]
	v_mfma_f32_16x16x32_bf16 v[66:69], v[156:159], v[206:209], v[66:69]
	v_mfma_f32_16x16x32_bf16 v[94:97], v[152:155], v[186:189], v[94:97]
	v_mfma_f32_16x16x32_bf16 v[90:93], v[162:165], v[186:189], v[90:93]
	v_mfma_f32_16x16x32_bf16 v[86:89], v[152:155], v[194:197], v[86:89]
	v_mfma_f32_16x16x32_bf16 v[82:85], v[162:165], v[194:197], v[82:85]
	v_mfma_f32_16x16x32_bf16 v[78:81], v[152:155], v[202:205], v[78:81]
	v_mfma_f32_16x16x32_bf16 v[74:77], v[162:165], v[202:205], v[74:77]
	v_mfma_f32_16x16x32_bf16 v[70:73], v[152:155], v[210:213], v[70:73]
	v_mfma_f32_16x16x32_bf16 v[66:69], v[162:165], v[210:213], v[66:69]
	s_setprio 0
	s_setprio 1
	v_mfma_f32_16x16x32_bf16 v[30:33], v[166:169], v[182:185], v[30:33]
	v_mfma_f32_16x16x32_bf16 v[26:29], v[174:177], v[182:185], v[26:29]
	v_mfma_f32_16x16x32_bf16 v[22:25], v[166:169], v[190:193], v[22:25]
	v_mfma_f32_16x16x32_bf16 v[18:21], v[174:177], v[190:193], v[18:21]
	v_mfma_f32_16x16x32_bf16 v[14:17], v[166:169], v[198:201], v[14:17]
	v_mfma_f32_16x16x32_bf16 v[10:13], v[174:177], v[198:201], v[10:13]
	v_mfma_f32_16x16x32_bf16 v[6:9], v[166:169], v[206:209], v[6:9]
	v_mfma_f32_16x16x32_bf16 v[0:3], v[174:177], v[206:209], v[0:3]
	v_mfma_f32_16x16x32_bf16 v[30:33], v[170:173], v[186:189], v[30:33]
	v_mfma_f32_16x16x32_bf16 v[26:29], v[178:181], v[186:189], v[26:29]
	v_mfma_f32_16x16x32_bf16 v[22:25], v[170:173], v[194:197], v[22:25]
	v_mfma_f32_16x16x32_bf16 v[18:21], v[178:181], v[194:197], v[18:21]
	v_mfma_f32_16x16x32_bf16 v[14:17], v[170:173], v[202:205], v[14:17]
	v_mfma_f32_16x16x32_bf16 v[10:13], v[178:181], v[202:205], v[10:13]
	v_mfma_f32_16x16x32_bf16 v[6:9], v[170:173], v[210:213], v[6:9]
	v_mfma_f32_16x16x32_bf16 v[0:3], v[178:181], v[210:213], v[0:3]
	s_setprio 0
	s_barrier
	s_add_i32 s61, 32, 0x18000
	s_add_i32 s65, 32, 0x1c000
	v_add_u32_e32 v162, s61, v160
	v_add_u32_e32 v178, s65, v160
	ds_read_b128 v[148:151], v162
	ds_read_b128 v[152:155], v162 offset:1024
	ds_read_b128 v[156:159], v162 offset:2048
	ds_read_b128 v[162:165], v162 offset:3072
	ds_read_b128 v[166:169], v178
	ds_read_b128 v[170:173], v178 offset:1024
	ds_read_b128 v[174:177], v178 offset:2048
	ds_read_b128 v[178:181], v178 offset:3072
	s_add_u32 s74, s74, 0x40000
	s_addc_u32 s75, s75, 0
	s_mov_b32 m0, s87
	v_lshl_add_u64 v[222:223], s[74:75], 0, v[136:137]
	ds_read_b128 v[182:185], v161 offset:32768
	ds_read_b128 v[186:189], v161 offset:33792
	ds_read_b128 v[190:193], v161 offset:34816
	ds_read_b128 v[194:197], v161 offset:35840
	ds_read_b128 v[198:201], v161 offset:36864
	ds_read_b128 v[202:205], v161 offset:37888
	ds_read_b128 v[206:209], v161 offset:38912
	ds_read_b128 v[210:213], v161 offset:39936
	global_load_lds_dwordx4 v[222:223], off
	v_lshl_add_u64 v[222:223], s[74:75], 0, v[132:133]
	s_mov_b32 m0, s16
	s_nop 0
	global_load_lds_dwordx4 v[222:223], off
	s_waitcnt vmcnt(8)
	s_waitcnt lgkmcnt(0)
	s_barrier
	s_setprio 1
	s_waitcnt lgkmcnt(0)
	v_mfma_f32_16x16x32_bf16 v[122:125], v[148:151], v[182:185], v[122:125]
	v_mfma_f32_16x16x32_bf16 v[126:129], v[156:159], v[182:185], v[126:129]
	v_mfma_f32_16x16x32_bf16 v[118:121], v[148:151], v[190:193], v[118:121]
	v_mfma_f32_16x16x32_bf16 v[114:117], v[156:159], v[190:193], v[114:117]
	v_mfma_f32_16x16x32_bf16 v[110:113], v[148:151], v[198:201], v[110:113]
	v_mfma_f32_16x16x32_bf16 v[106:109], v[156:159], v[198:201], v[106:109]
	v_mfma_f32_16x16x32_bf16 v[102:105], v[148:151], v[206:209], v[102:105]
	v_mfma_f32_16x16x32_bf16 v[98:101], v[156:159], v[206:209], v[98:101]
	v_mfma_f32_16x16x32_bf16 v[122:125], v[152:155], v[186:189], v[122:125]
	v_mfma_f32_16x16x32_bf16 v[126:129], v[162:165], v[186:189], v[126:129]
	v_mfma_f32_16x16x32_bf16 v[118:121], v[152:155], v[194:197], v[118:121]
	v_mfma_f32_16x16x32_bf16 v[114:117], v[162:165], v[194:197], v[114:117]
	v_mfma_f32_16x16x32_bf16 v[110:113], v[152:155], v[202:205], v[110:113]
	v_mfma_f32_16x16x32_bf16 v[106:109], v[162:165], v[202:205], v[106:109]
	v_mfma_f32_16x16x32_bf16 v[102:105], v[152:155], v[210:213], v[102:105]
	v_mfma_f32_16x16x32_bf16 v[98:101], v[162:165], v[210:213], v[98:101]
	s_setprio 0
	s_setprio 1
	v_mfma_f32_16x16x32_bf16 v[62:65], v[166:169], v[182:185], v[62:65]
	v_mfma_f32_16x16x32_bf16 v[58:61], v[174:177], v[182:185], v[58:61]
	v_mfma_f32_16x16x32_bf16 v[54:57], v[166:169], v[190:193], v[54:57]
	v_mfma_f32_16x16x32_bf16 v[50:53], v[174:177], v[190:193], v[50:53]
	v_mfma_f32_16x16x32_bf16 v[46:49], v[166:169], v[198:201], v[46:49]
	v_mfma_f32_16x16x32_bf16 v[42:45], v[174:177], v[198:201], v[42:45]
	v_mfma_f32_16x16x32_bf16 v[38:41], v[166:169], v[206:209], v[38:41]
	v_mfma_f32_16x16x32_bf16 v[34:37], v[174:177], v[206:209], v[34:37]
	v_mfma_f32_16x16x32_bf16 v[62:65], v[170:173], v[186:189], v[62:65]
	v_mfma_f32_16x16x32_bf16 v[58:61], v[178:181], v[186:189], v[58:61]
	v_mfma_f32_16x16x32_bf16 v[54:57], v[170:173], v[194:197], v[54:57]
	v_mfma_f32_16x16x32_bf16 v[50:53], v[178:181], v[194:197], v[50:53]
	v_mfma_f32_16x16x32_bf16 v[46:49], v[170:173], v[202:205], v[46:49]
	v_mfma_f32_16x16x32_bf16 v[42:45], v[178:181], v[202:205], v[42:45]
	v_mfma_f32_16x16x32_bf16 v[38:41], v[170:173], v[210:213], v[38:41]
	v_mfma_f32_16x16x32_bf16 v[34:37], v[178:181], v[210:213], v[34:37]
	s_setprio 0
	s_barrier
	s_add_i32 s61, s61, s84
	v_lshl_add_u64 v[214:215], v[214:215], 0, s[54:55]
	s_mov_b32 m0, s61
	ds_read_b128 v[182:185], v161 offset:49152
	ds_read_b128 v[186:189], v161 offset:50176
	ds_read_b128 v[190:193], v161 offset:51200
	ds_read_b128 v[194:197], v161 offset:52224
	ds_read_b128 v[198:201], v161 offset:53248
	ds_read_b128 v[202:205], v161 offset:54272
	ds_read_b128 v[206:209], v161 offset:55296
	ds_read_b128 v[210:213], v161 offset:56320
	global_load_lds_dwordx4 v[214:215], off
	s_add_i32 m0, s61, 0x2000
	s_add_u32 s8, s8, 0x40080
	v_lshl_add_u64 v[214:215], v[216:217], 0, s[54:55]
	s_addc_u32 s9, s9, 0
	s_add_i32 s61, s65, s84
	global_load_lds_dwordx4 v[214:215], off
	v_lshl_add_u64 v[214:215], s[8:9], 0, v[134:135]
	s_mov_b32 m0, s61
	s_nop 0
	global_load_lds_dwordx4 v[214:215], off
	v_lshl_add_u64 v[214:215], s[8:9], 0, v[130:131]
	s_add_i32 m0, s61, 0x2000
	s_nop 0
	global_load_lds_dwordx4 v[214:215], off
	v_lshl_add_u64 v[214:215], v[218:219], 0, s[54:55]
	s_mov_b32 m0, s95
	s_nop 0
	global_load_lds_dwordx4 v[214:215], off
	v_lshl_add_u64 v[214:215], v[220:221], 0, s[54:55]
	s_mov_b32 m0, s35
	s_nop 0
	global_load_lds_dwordx4 v[214:215], off
	s_waitcnt vmcnt(8)
	s_waitcnt lgkmcnt(0)
	s_barrier
	s_setprio 1
	s_waitcnt lgkmcnt(0)
	v_mfma_f32_16x16x32_bf16 v[94:97], v[148:151], v[182:185], v[94:97]
	v_mfma_f32_16x16x32_bf16 v[90:93], v[156:159], v[182:185], v[90:93]
	v_mfma_f32_16x16x32_bf16 v[86:89], v[148:151], v[190:193], v[86:89]
	v_mfma_f32_16x16x32_bf16 v[82:85], v[156:159], v[190:193], v[82:85]
	v_mfma_f32_16x16x32_bf16 v[78:81], v[148:151], v[198:201], v[78:81]
	v_mfma_f32_16x16x32_bf16 v[74:77], v[156:159], v[198:201], v[74:77]
	v_mfma_f32_16x16x32_bf16 v[70:73], v[148:151], v[206:209], v[70:73]
	v_mfma_f32_16x16x32_bf16 v[66:69], v[156:159], v[206:209], v[66:69]
	v_mfma_f32_16x16x32_bf16 v[94:97], v[152:155], v[186:189], v[94:97]
	v_mfma_f32_16x16x32_bf16 v[90:93], v[162:165], v[186:189], v[90:93]
	v_mfma_f32_16x16x32_bf16 v[86:89], v[152:155], v[194:197], v[86:89]
	v_mfma_f32_16x16x32_bf16 v[82:85], v[162:165], v[194:197], v[82:85]
	v_mfma_f32_16x16x32_bf16 v[78:81], v[152:155], v[202:205], v[78:81]
	v_mfma_f32_16x16x32_bf16 v[74:77], v[162:165], v[202:205], v[74:77]
	v_mfma_f32_16x16x32_bf16 v[70:73], v[152:155], v[210:213], v[70:73]
	v_mfma_f32_16x16x32_bf16 v[66:69], v[162:165], v[210:213], v[66:69]
	s_setprio 0
	s_setprio 1
	v_mfma_f32_16x16x32_bf16 v[30:33], v[166:169], v[182:185], v[30:33]
	v_mfma_f32_16x16x32_bf16 v[26:29], v[174:177], v[182:185], v[26:29]
	v_mfma_f32_16x16x32_bf16 v[22:25], v[166:169], v[190:193], v[22:25]
	v_mfma_f32_16x16x32_bf16 v[18:21], v[174:177], v[190:193], v[18:21]
	v_mfma_f32_16x16x32_bf16 v[14:17], v[166:169], v[198:201], v[14:17]
	v_mfma_f32_16x16x32_bf16 v[10:13], v[174:177], v[198:201], v[10:13]
	v_mfma_f32_16x16x32_bf16 v[6:9], v[166:169], v[206:209], v[6:9]
	v_mfma_f32_16x16x32_bf16 v[0:3], v[174:177], v[206:209], v[0:3]
	v_mfma_f32_16x16x32_bf16 v[30:33], v[170:173], v[186:189], v[30:33]
	v_mfma_f32_16x16x32_bf16 v[26:29], v[178:181], v[186:189], v[26:29]
	v_mfma_f32_16x16x32_bf16 v[22:25], v[170:173], v[194:197], v[22:25]
	v_mfma_f32_16x16x32_bf16 v[18:21], v[178:181], v[194:197], v[18:21]
	v_mfma_f32_16x16x32_bf16 v[14:17], v[170:173], v[202:205], v[14:17]
	v_mfma_f32_16x16x32_bf16 v[10:13], v[178:181], v[202:205], v[10:13]
	v_mfma_f32_16x16x32_bf16 v[6:9], v[170:173], v[210:213], v[6:9]
	v_mfma_f32_16x16x32_bf16 v[0:3], v[178:181], v[210:213], v[0:3]
	s_setprio 0
	s_add_u32 s6, s6, 0x100
	s_addc_u32 s7, s7, 0
	s_add_u32 s56, s56, 0x100
	s_addc_u32 s57, s57, 0
	s_cmp_ge_i32 s60, s50
	s_mov_b32 s8, s60
	s_cbranch_scc1 .Lrotx_0
	s_add_i32 s60, s8, 2
	s_add_u32 s9, s6, 0xfffc0080
	s_addc_u32 s61, s7, -1
	s_add_i32 s65, 32, 0x10000
	s_cmp_eq_u32 s17, s8
	s_cselect_b32 s75, s15, s61
	s_cselect_b32 s74, s21, s9
	s_cselect_b32 s9, s44, s57
	s_cselect_b32 s8, s45, s56
	s_add_i32 s61, 32, 0x14000
	s_barrier
	s_branch .Lrot_0
.Lrotx_0:
	s_barrier
	s_movk_i32 s65, 0x340

.Lrot_1:
	v_add_u32_e32 v166, s79, v152
	v_add_u32_e32 v182, s80, v152
	ds_read_b128 v[154:157], v166
	ds_read_b128 v[158:161], v166 offset:1024
	ds_read_b128 v[162:165], v166 offset:2048
	ds_read_b128 v[166:169], v166 offset:3072
	ds_read_b128 v[170:173], v182
	ds_read_b128 v[174:177], v182 offset:1024
	ds_read_b128 v[178:181], v182 offset:2048
	ds_read_b128 v[182:185], v182 offset:3072
	v_lshl_add_u64 v[218:219], v[148:149], 0, s[20:21]
	s_add_i32 m0, s17, 0xc000
	ds_read_b128 v[186:189], v153
	ds_read_b128 v[190:193], v153 offset:1024
	ds_read_b128 v[194:197], v153 offset:2048
	ds_read_b128 v[198:201], v153 offset:3072
	ds_read_b128 v[202:205], v153 offset:4096
	ds_read_b128 v[206:209], v153 offset:5120
	ds_read_b128 v[210:213], v153 offset:6144
	ds_read_b128 v[214:217], v153 offset:7168
	global_load_lds_dwordx4 v[218:219], off
	v_lshl_add_u64 v[218:219], v[150:151], 0, s[20:21]
	s_add_i32 m0, s17, 0xe000
	s_nop 0
	global_load_lds_dwordx4 v[218:219], off
	s_waitcnt vmcnt(8)
	s_waitcnt lgkmcnt(0)
	s_barrier
	s_setprio 1
	s_waitcnt lgkmcnt(0)
	v_mfma_f32_16x16x32_bf16 v[126:129], v[154:157], v[186:189], v[126:129]
	v_mfma_f32_16x16x32_bf16 v[122:125], v[162:165], v[186:189], v[122:125]
	v_mfma_f32_16x16x32_bf16 v[118:121], v[154:157], v[194:197], v[118:121]
	v_mfma_f32_16x16x32_bf16 v[114:117], v[162:165], v[194:197], v[114:117]
	v_mfma_f32_16x16x32_bf16 v[110:113], v[154:157], v[202:205], v[110:113]
	v_mfma_f32_16x16x32_bf16 v[106:109], v[162:165], v[202:205], v[106:109]
	v_mfma_f32_16x16x32_bf16 v[102:105], v[154:157], v[210:213], v[102:105]
	v_mfma_f32_16x16x32_bf16 v[98:101], v[162:165], v[210:213], v[98:101]
	v_mfma_f32_16x16x32_bf16 v[126:129], v[158:161], v[190:193], v[126:129]
	v_mfma_f32_16x16x32_bf16 v[122:125], v[166:169], v[190:193], v[122:125]
	v_mfma_f32_16x16x32_bf16 v[118:121], v[158:161], v[198:201], v[118:121]
	v_mfma_f32_16x16x32_bf16 v[114:117], v[166:169], v[198:201], v[114:117]
	v_mfma_f32_16x16x32_bf16 v[110:113], v[158:161], v[206:209], v[110:113]
	v_mfma_f32_16x16x32_bf16 v[106:109], v[166:169], v[206:209], v[106:109]
	v_mfma_f32_16x16x32_bf16 v[102:105], v[158:161], v[214:217], v[102:105]
	v_mfma_f32_16x16x32_bf16 v[98:101], v[166:169], v[214:217], v[98:101]
	s_setprio 0
	s_setprio 1
	v_mfma_f32_16x16x32_bf16 v[62:65], v[170:173], v[186:189], v[62:65]
	v_mfma_f32_16x16x32_bf16 v[58:61], v[178:181], v[186:189], v[58:61]
	v_mfma_f32_16x16x32_bf16 v[54:57], v[170:173], v[194:197], v[54:57]
	v_mfma_f32_16x16x32_bf16 v[50:53], v[178:181], v[194:197], v[50:53]
	v_mfma_f32_16x16x32_bf16 v[46:49], v[170:173], v[202:205], v[46:49]
	v_mfma_f32_16x16x32_bf16 v[42:45], v[178:181], v[202:205], v[42:45]
	v_mfma_f32_16x16x32_bf16 v[38:41], v[170:173], v[210:213], v[38:41]
	v_mfma_f32_16x16x32_bf16 v[34:37], v[178:181], v[210:213], v[34:37]
	v_mfma_f32_16x16x32_bf16 v[62:65], v[174:177], v[190:193], v[62:65]
	v_mfma_f32_16x16x32_bf16 v[58:61], v[182:185], v[190:193], v[58:61]
	v_mfma_f32_16x16x32_bf16 v[54:57], v[174:177], v[198:201], v[54:57]
	v_mfma_f32_16x16x32_bf16 v[50:53], v[182:185], v[198:201], v[50:53]
	v_mfma_f32_16x16x32_bf16 v[46:49], v[174:177], v[206:209], v[46:49]
	v_mfma_f32_16x16x32_bf16 v[42:45], v[182:185], v[206:209], v[42:45]
	v_mfma_f32_16x16x32_bf16 v[38:41], v[174:177], v[214:217], v[38:41]
	v_mfma_f32_16x16x32_bf16 v[34:37], v[182:185], v[214:217], v[34:37]
	s_setprio 0
	s_barrier
	s_add_i32 s20, s79, s16
	v_lshl_add_u64 v[218:219], s[70:71], 0, v[134:135]
	s_mov_b32 m0, s20
	ds_read_b128 v[186:189], v153 offset:16384
	ds_read_b128 v[190:193], v153 offset:17408
	ds_read_b128 v[194:197], v153 offset:18432
	ds_read_b128 v[198:201], v153 offset:19456
	ds_read_b128 v[202:205], v153 offset:20480
	ds_read_b128 v[206:209], v153 offset:21504
	ds_read_b128 v[210:213], v153 offset:22528
	ds_read_b128 v[214:217], v153 offset:23552
	global_load_lds_dwordx4 v[218:219], off
	s_add_i32 m0, s20, 0x2000
	s_add_u32 s20, s70, 0x40000
	v_lshl_add_u64 v[220:221], s[70:71], 0, v[130:131]
	s_addc_u32 s21, s71, 0
	s_add_i32 s79, s80, s16
	global_load_lds_dwordx4 v[220:221], off
	v_lshl_add_u64 v[222:223], s[20:21], 0, v[134:135]
	s_mov_b32 m0, s79
	v_lshl_add_u64 v[224:225], s[72:73], 0, v[132:133]
	global_load_lds_dwordx4 v[222:223], off
	v_lshl_add_u64 v[222:223], s[20:21], 0, v[130:131]
	s_add_i32 m0, s79, 0x2000
	s_nop 0
	global_load_lds_dwordx4 v[222:223], off
	v_lshl_add_u64 v[222:223], s[72:73], 0, v[136:137]
	s_mov_b32 m0, s17
	s_nop 0
	global_load_lds_dwordx4 v[222:223], off
	s_mov_b32 m0, s18
	s_nop 0
	global_load_lds_dwordx4 v[224:225], off
	s_waitcnt vmcnt(8)
	s_waitcnt lgkmcnt(0)
	s_barrier
	s_setprio 1
	s_waitcnt lgkmcnt(0)
	v_mfma_f32_16x16x32_bf16 v[94:97], v[154:157], v[186:189], v[94:97]
	v_mfma_f32_16x16x32_bf16 v[90:93], v[162:165], v[186:189], v[90:93]
	v_mfma_f32_16x16x32_bf16 v[86:89], v[154:157], v[194:197], v[86:89]
	v_mfma_f32_16x16x32_bf16 v[82:85], v[162:165], v[194:197], v[82:85]
	v_mfma_f32_16x16x32_bf16 v[78:81], v[154:157], v[202:205], v[78:81]
	v_mfma_f32_16x16x32_bf16 v[74:77], v[162:165], v[202:205], v[74:77]
	v_mfma_f32_16x16x32_bf16 v[70:73], v[154:157], v[210:213], v[70:73]
	v_mfma_f32_16x16x32_bf16 v[66:69], v[162:165], v[210:213], v[66:69]
	v_mfma_f32_16x16x32_bf16 v[94:97], v[158:161], v[190:193], v[94:97]
	v_mfma_f32_16x16x32_bf16 v[90:93], v[166:169], v[190:193], v[90:93]
	v_mfma_f32_16x16x32_bf16 v[86:89], v[158:161], v[198:201], v[86:89]
	v_mfma_f32_16x16x32_bf16 v[82:85], v[166:169], v[198:201], v[82:85]
	v_mfma_f32_16x16x32_bf16 v[78:81], v[158:161], v[206:209], v[78:81]
	v_mfma_f32_16x16x32_bf16 v[74:77], v[166:169], v[206:209], v[74:77]
	v_mfma_f32_16x16x32_bf16 v[70:73], v[158:161], v[214:217], v[70:73]
	v_mfma_f32_16x16x32_bf16 v[66:69], v[166:169], v[214:217], v[66:69]
	s_setprio 0
	s_setprio 1
	v_mfma_f32_16x16x32_bf16 v[30:33], v[170:173], v[186:189], v[30:33]
	v_mfma_f32_16x16x32_bf16 v[26:29], v[178:181], v[186:189], v[26:29]
	v_mfma_f32_16x16x32_bf16 v[22:25], v[170:173], v[194:197], v[22:25]
	v_mfma_f32_16x16x32_bf16 v[18:21], v[178:181], v[194:197], v[18:21]
	v_mfma_f32_16x16x32_bf16 v[14:17], v[170:173], v[202:205], v[14:17]
	v_mfma_f32_16x16x32_bf16 v[10:13], v[178:181], v[202:205], v[10:13]
	v_mfma_f32_16x16x32_bf16 v[6:9], v[170:173], v[210:213], v[6:9]
	v_mfma_f32_16x16x32_bf16 v[0:3], v[178:181], v[210:213], v[0:3]
	v_mfma_f32_16x16x32_bf16 v[30:33], v[174:177], v[190:193], v[30:33]
	v_mfma_f32_16x16x32_bf16 v[26:29], v[182:185], v[190:193], v[26:29]
	v_mfma_f32_16x16x32_bf16 v[22:25], v[174:177], v[198:201], v[22:25]
	v_mfma_f32_16x16x32_bf16 v[18:21], v[182:185], v[198:201], v[18:21]
	v_mfma_f32_16x16x32_bf16 v[14:17], v[174:177], v[206:209], v[14:17]
	v_mfma_f32_16x16x32_bf16 v[10:13], v[182:185], v[206:209], v[10:13]
	v_mfma_f32_16x16x32_bf16 v[6:9], v[174:177], v[214:217], v[6:9]
	v_mfma_f32_16x16x32_bf16 v[0:3], v[182:185], v[214:217], v[0:3]
	s_setprio 0
	s_barrier
	s_add_i32 s79, 32, 0x18000
	s_add_i32 s80, 32, 0x1c000
	v_add_u32_e32 v166, s79, v152
	v_add_u32_e32 v182, s80, v152
	ds_read_b128 v[154:157], v166
	ds_read_b128 v[158:161], v166 offset:1024
	ds_read_b128 v[162:165], v166 offset:2048
	ds_read_b128 v[166:169], v166 offset:3072
	ds_read_b128 v[170:173], v182
	ds_read_b128 v[174:177], v182 offset:1024
	ds_read_b128 v[178:181], v182 offset:2048
	ds_read_b128 v[182:185], v182 offset:3072
	s_add_u32 s20, s72, 0x40000
	s_addc_u32 s21, s73, 0
	s_mov_b32 m0, s35
	v_lshl_add_u64 v[226:227], s[20:21], 0, v[136:137]
	ds_read_b128 v[186:189], v153 offset:32768
	ds_read_b128 v[190:193], v153 offset:33792
	ds_read_b128 v[194:197], v153 offset:34816
	ds_read_b128 v[198:201], v153 offset:35840
	ds_read_b128 v[202:205], v153 offset:36864
	ds_read_b128 v[206:209], v153 offset:37888
	ds_read_b128 v[210:213], v153 offset:38912
	ds_read_b128 v[214:217], v153 offset:39936
	global_load_lds_dwordx4 v[226:227], off
	v_lshl_add_u64 v[226:227], s[20:21], 0, v[132:133]
	s_mov_b32 m0, s44
	s_nop 0
	global_load_lds_dwordx4 v[226:227], off
	s_waitcnt vmcnt(8)
	s_waitcnt lgkmcnt(0)
	s_barrier
	s_setprio 1
	s_waitcnt lgkmcnt(0)
	v_mfma_f32_16x16x32_bf16 v[126:129], v[154:157], v[186:189], v[126:129]
	v_mfma_f32_16x16x32_bf16 v[122:125], v[162:165], v[186:189], v[122:125]
	v_mfma_f32_16x16x32_bf16 v[118:121], v[154:157], v[194:197], v[118:121]
	v_mfma_f32_16x16x32_bf16 v[114:117], v[162:165], v[194:197], v[114:117]
	v_mfma_f32_16x16x32_bf16 v[110:113], v[154:157], v[202:205], v[110:113]
	v_mfma_f32_16x16x32_bf16 v[106:109], v[162:165], v[202:205], v[106:109]
	v_mfma_f32_16x16x32_bf16 v[102:105], v[154:157], v[210:213], v[102:105]
	v_mfma_f32_16x16x32_bf16 v[98:101], v[162:165], v[210:213], v[98:101]
	v_mfma_f32_16x16x32_bf16 v[126:129], v[158:161], v[190:193], v[126:129]
	v_mfma_f32_16x16x32_bf16 v[122:125], v[166:169], v[190:193], v[122:125]
	v_mfma_f32_16x16x32_bf16 v[118:121], v[158:161], v[198:201], v[118:121]
	v_mfma_f32_16x16x32_bf16 v[114:117], v[166:169], v[198:201], v[114:117]
	v_mfma_f32_16x16x32_bf16 v[110:113], v[158:161], v[206:209], v[110:113]
	v_mfma_f32_16x16x32_bf16 v[106:109], v[166:169], v[206:209], v[106:109]
	v_mfma_f32_16x16x32_bf16 v[102:105], v[158:161], v[214:217], v[102:105]
	v_mfma_f32_16x16x32_bf16 v[98:101], v[166:169], v[214:217], v[98:101]
	s_setprio 0
	s_setprio 1
	v_mfma_f32_16x16x32_bf16 v[62:65], v[170:173], v[186:189], v[62:65]
	v_mfma_f32_16x16x32_bf16 v[58:61], v[178:181], v[186:189], v[58:61]
	v_mfma_f32_16x16x32_bf16 v[54:57], v[170:173], v[194:197], v[54:57]
	v_mfma_f32_16x16x32_bf16 v[50:53], v[178:181], v[194:197], v[50:53]
	v_mfma_f32_16x16x32_bf16 v[46:49], v[170:173], v[202:205], v[46:49]
	v_mfma_f32_16x16x32_bf16 v[42:45], v[178:181], v[202:205], v[42:45]
	v_mfma_f32_16x16x32_bf16 v[38:41], v[170:173], v[210:213], v[38:41]
	v_mfma_f32_16x16x32_bf16 v[34:37], v[178:181], v[210:213], v[34:37]
	v_mfma_f32_16x16x32_bf16 v[62:65], v[174:177], v[190:193], v[62:65]
	v_mfma_f32_16x16x32_bf16 v[58:61], v[182:185], v[190:193], v[58:61]
	v_mfma_f32_16x16x32_bf16 v[54:57], v[174:177], v[198:201], v[54:57]
	v_mfma_f32_16x16x32_bf16 v[50:53], v[182:185], v[198:201], v[50:53]
	v_mfma_f32_16x16x32_bf16 v[46:49], v[174:177], v[206:209], v[46:49]
	v_mfma_f32_16x16x32_bf16 v[42:45], v[182:185], v[206:209], v[42:45]
	v_mfma_f32_16x16x32_bf16 v[38:41], v[174:177], v[214:217], v[38:41]
	v_mfma_f32_16x16x32_bf16 v[34:37], v[182:185], v[214:217], v[34:37]
	s_setprio 0
	s_barrier
	s_add_i32 s20, s79, s16
	v_lshl_add_u64 v[218:219], v[218:219], 0, s[54:55]
	s_mov_b32 m0, s20
	ds_read_b128 v[186:189], v153 offset:49152
	ds_read_b128 v[190:193], v153 offset:50176
	ds_read_b128 v[194:197], v153 offset:51200
	ds_read_b128 v[198:201], v153 offset:52224
	ds_read_b128 v[202:205], v153 offset:53248
	ds_read_b128 v[206:209], v153 offset:54272
	ds_read_b128 v[210:213], v153 offset:55296
	ds_read_b128 v[214:217], v153 offset:56320
	global_load_lds_dwordx4 v[218:219], off
	s_add_i32 m0, s20, 0x2000
	s_add_u32 s20, s70, 0x40080
	v_lshl_add_u64 v[218:219], v[220:221], 0, s[54:55]
	s_addc_u32 s21, s71, 0
	s_add_i32 s70, s80, s16
	global_load_lds_dwordx4 v[218:219], off
	v_lshl_add_u64 v[218:219], s[20:21], 0, v[134:135]
	s_mov_b32 m0, s70
	s_nop 0
	global_load_lds_dwordx4 v[218:219], off
	v_lshl_add_u64 v[218:219], s[20:21], 0, v[130:131]
	s_add_i32 m0, s70, 0x2000
	s_nop 0
	global_load_lds_dwordx4 v[218:219], off
	v_lshl_add_u64 v[218:219], v[222:223], 0, s[54:55]
	s_mov_b32 m0, s51
	s_nop 0
	global_load_lds_dwordx4 v[218:219], off
	v_lshl_add_u64 v[218:219], v[224:225], 0, s[54:55]
	s_mov_b32 m0, s56
	s_nop 0
	global_load_lds_dwordx4 v[218:219], off
	s_waitcnt vmcnt(8)
	s_waitcnt lgkmcnt(0)
	s_barrier
	s_setprio 1
	s_waitcnt lgkmcnt(0)
	v_mfma_f32_16x16x32_bf16 v[94:97], v[154:157], v[186:189], v[94:97]
	v_mfma_f32_16x16x32_bf16 v[90:93], v[162:165], v[186:189], v[90:93]
	v_mfma_f32_16x16x32_bf16 v[86:89], v[154:157], v[194:197], v[86:89]
	v_mfma_f32_16x16x32_bf16 v[82:85], v[162:165], v[194:197], v[82:85]
	v_mfma_f32_16x16x32_bf16 v[78:81], v[154:157], v[202:205], v[78:81]
	v_mfma_f32_16x16x32_bf16 v[74:77], v[162:165], v[202:205], v[74:77]
	v_mfma_f32_16x16x32_bf16 v[70:73], v[154:157], v[210:213], v[70:73]
	v_mfma_f32_16x16x32_bf16 v[66:69], v[162:165], v[210:213], v[66:69]
	v_mfma_f32_16x16x32_bf16 v[94:97], v[158:161], v[190:193], v[94:97]
	v_mfma_f32_16x16x32_bf16 v[90:93], v[166:169], v[190:193], v[90:93]
	v_mfma_f32_16x16x32_bf16 v[86:89], v[158:161], v[198:201], v[86:89]
	v_mfma_f32_16x16x32_bf16 v[82:85], v[166:169], v[198:201], v[82:85]
	v_mfma_f32_16x16x32_bf16 v[78:81], v[158:161], v[206:209], v[78:81]
	v_mfma_f32_16x16x32_bf16 v[74:77], v[166:169], v[206:209], v[74:77]
	v_mfma_f32_16x16x32_bf16 v[70:73], v[158:161], v[214:217], v[70:73]
	v_mfma_f32_16x16x32_bf16 v[66:69], v[166:169], v[214:217], v[66:69]
	s_setprio 0
	s_setprio 1
	v_mfma_f32_16x16x32_bf16 v[30:33], v[170:173], v[186:189], v[30:33]
	v_mfma_f32_16x16x32_bf16 v[26:29], v[178:181], v[186:189], v[26:29]
	v_mfma_f32_16x16x32_bf16 v[22:25], v[170:173], v[194:197], v[22:25]
	v_mfma_f32_16x16x32_bf16 v[18:21], v[178:181], v[194:197], v[18:21]
	v_mfma_f32_16x16x32_bf16 v[14:17], v[170:173], v[202:205], v[14:17]
	v_mfma_f32_16x16x32_bf16 v[10:13], v[178:181], v[202:205], v[10:13]
	v_mfma_f32_16x16x32_bf16 v[6:9], v[170:173], v[210:213], v[6:9]
	v_mfma_f32_16x16x32_bf16 v[0:3], v[178:181], v[210:213], v[0:3]
	v_mfma_f32_16x16x32_bf16 v[30:33], v[174:177], v[190:193], v[30:33]
	v_mfma_f32_16x16x32_bf16 v[26:29], v[182:185], v[190:193], v[26:29]
	v_mfma_f32_16x16x32_bf16 v[22:25], v[174:177], v[198:201], v[22:25]
	v_mfma_f32_16x16x32_bf16 v[18:21], v[182:185], v[198:201], v[18:21]
	v_mfma_f32_16x16x32_bf16 v[14:17], v[174:177], v[206:209], v[14:17]
	v_mfma_f32_16x16x32_bf16 v[10:13], v[182:185], v[206:209], v[10:13]
	v_mfma_f32_16x16x32_bf16 v[6:9], v[174:177], v[214:217], v[6:9]
	v_mfma_f32_16x16x32_bf16 v[0:3], v[182:185], v[214:217], v[0:3]
	s_setprio 0
	s_cmp_ge_i32 s78, s50
	s_mov_b64 s[20:21], s[22:23]
	s_mov_b32 s70, s78
	s_cbranch_scc1 .Lrotx_1
	s_add_i32 s78, s70, 2
	s_add_u32 s22, s20, 0x100
	s_addc_u32 s23, s21, 0
	s_add_u32 s71, s76, s20
	s_addc_u32 s72, s77, s21
	s_add_i32 s79, 32, 0x10000
	s_cmp_eq_u32 s19, s70
	s_cselect_b32 s70, 0, s22
	s_cselect_b32 s73, s74, s72
	s_cselect_b32 s72, s75, s71
	s_cselect_b32 s71, 0, s23
	s_add_u32 s70, s0, s70
	s_addc_u32 s71, s1, s71
	s_add_i32 s80, 32, 0x14000
	s_barrier
	s_branch .Lrot_1
.Lrotx_1:
	s_barrier
.LBB0_722:
	s_and_b64 vcc, exec, s[8:9]
	s_cbranch_vccz .LBB0_724
	s_barrier

.Lrot_2:
	v_add_u32_e32 v162, s86, v148
	v_add_u32_e32 v178, s90, v148
	ds_read_b128 v[150:153], v162
	ds_read_b128 v[154:157], v162 offset:1024
	ds_read_b128 v[158:161], v162 offset:2048
	ds_read_b128 v[162:165], v162 offset:3072
	ds_read_b128 v[166:169], v178
	ds_read_b128 v[170:173], v178 offset:1024
	ds_read_b128 v[174:177], v178 offset:2048
	ds_read_b128 v[178:181], v178 offset:3072
	v_lshl_add_u64 v[214:215], s[70:71], 0, v[144:145]
	s_add_i32 m0, s7, 0xc000
	ds_read_b128 v[182:185], v149
	ds_read_b128 v[186:189], v149 offset:1024
	ds_read_b128 v[190:193], v149 offset:2048
	ds_read_b128 v[194:197], v149 offset:3072
	ds_read_b128 v[198:201], v149 offset:4096
	ds_read_b128 v[202:205], v149 offset:5120
	ds_read_b128 v[206:209], v149 offset:6144
	ds_read_b128 v[210:213], v149 offset:7168
	global_load_lds_dwordx4 v[214:215], off
	v_lshl_add_u64 v[214:215], s[70:71], 0, v[146:147]
	s_add_i32 m0, s7, 0xe000
	s_nop 0
	global_load_lds_dwordx4 v[214:215], off
	s_waitcnt vmcnt(8)
	s_waitcnt lgkmcnt(0)
	s_barrier
	s_setprio 1
	s_waitcnt lgkmcnt(0)
	v_mfma_f32_16x16x32_bf16 v[126:129], v[150:153], v[182:185], v[126:129]
	v_mfma_f32_16x16x32_bf16 v[122:125], v[158:161], v[182:185], v[122:125]
	v_mfma_f32_16x16x32_bf16 v[118:121], v[150:153], v[190:193], v[118:121]
	v_mfma_f32_16x16x32_bf16 v[114:117], v[158:161], v[190:193], v[114:117]
	v_mfma_f32_16x16x32_bf16 v[110:113], v[150:153], v[198:201], v[110:113]
	v_mfma_f32_16x16x32_bf16 v[106:109], v[158:161], v[198:201], v[106:109]
	v_mfma_f32_16x16x32_bf16 v[102:105], v[150:153], v[206:209], v[102:105]
	v_mfma_f32_16x16x32_bf16 v[98:101], v[158:161], v[206:209], v[98:101]
	v_mfma_f32_16x16x32_bf16 v[126:129], v[154:157], v[186:189], v[126:129]
	v_mfma_f32_16x16x32_bf16 v[122:125], v[162:165], v[186:189], v[122:125]
	v_mfma_f32_16x16x32_bf16 v[118:121], v[154:157], v[194:197], v[118:121]
	v_mfma_f32_16x16x32_bf16 v[114:117], v[162:165], v[194:197], v[114:117]
	v_mfma_f32_16x16x32_bf16 v[110:113], v[154:157], v[202:205], v[110:113]
	v_mfma_f32_16x16x32_bf16 v[106:109], v[162:165], v[202:205], v[106:109]
	v_mfma_f32_16x16x32_bf16 v[102:105], v[154:157], v[210:213], v[102:105]
	v_mfma_f32_16x16x32_bf16 v[98:101], v[162:165], v[210:213], v[98:101]
	s_setprio 0
	s_setprio 1
	v_mfma_f32_16x16x32_bf16 v[62:65], v[166:169], v[182:185], v[62:65]
	v_mfma_f32_16x16x32_bf16 v[58:61], v[174:177], v[182:185], v[58:61]
	v_mfma_f32_16x16x32_bf16 v[54:57], v[166:169], v[190:193], v[54:57]
	v_mfma_f32_16x16x32_bf16 v[50:53], v[174:177], v[190:193], v[50:53]
	v_mfma_f32_16x16x32_bf16 v[46:49], v[166:169], v[198:201], v[46:49]
	v_mfma_f32_16x16x32_bf16 v[42:45], v[174:177], v[198:201], v[42:45]
	v_mfma_f32_16x16x32_bf16 v[38:41], v[166:169], v[206:209], v[38:41]
	v_mfma_f32_16x16x32_bf16 v[34:37], v[174:177], v[206:209], v[34:37]
	v_mfma_f32_16x16x32_bf16 v[62:65], v[170:173], v[186:189], v[62:65]
	v_mfma_f32_16x16x32_bf16 v[58:61], v[178:181], v[186:189], v[58:61]
	v_mfma_f32_16x16x32_bf16 v[54:57], v[170:173], v[194:197], v[54:57]
	v_mfma_f32_16x16x32_bf16 v[50:53], v[178:181], v[194:197], v[50:53]
	v_mfma_f32_16x16x32_bf16 v[46:49], v[170:173], v[202:205], v[46:49]
	v_mfma_f32_16x16x32_bf16 v[42:45], v[178:181], v[202:205], v[42:45]
	v_mfma_f32_16x16x32_bf16 v[38:41], v[170:173], v[210:213], v[38:41]
	v_mfma_f32_16x16x32_bf16 v[34:37], v[178:181], v[210:213], v[34:37]
	s_setprio 0
	s_barrier
	s_add_i32 s86, s86, s16
	v_lshl_add_u64 v[214:215], s[72:73], 0, v[132:133]
	s_mov_b32 m0, s86
	ds_read_b128 v[182:185], v149 offset:16384
	ds_read_b128 v[186:189], v149 offset:17408
	ds_read_b128 v[190:193], v149 offset:18432
	ds_read_b128 v[194:197], v149 offset:19456
	ds_read_b128 v[198:201], v149 offset:20480
	ds_read_b128 v[202:205], v149 offset:21504
	ds_read_b128 v[206:209], v149 offset:22528
	ds_read_b128 v[210:213], v149 offset:23552
	global_load_lds_dwordx4 v[214:215], off
	s_add_i32 m0, s86, 0x2000
	s_add_u32 s86, s72, 0x40000
	v_lshl_add_u64 v[216:217], s[72:73], 0, v[136:137]
	s_addc_u32 s87, s73, 0
	s_add_i32 s90, s90, s16
	global_load_lds_dwordx4 v[216:217], off
	v_lshl_add_u64 v[218:219], s[86:87], 0, v[132:133]
	s_mov_b32 m0, s90
	v_lshl_add_u64 v[220:221], s[74:75], 0, v[134:135]
	global_load_lds_dwordx4 v[218:219], off
	v_lshl_add_u64 v[218:219], s[86:87], 0, v[136:137]
	s_add_i32 m0, s90, 0x2000
	s_nop 0
	global_load_lds_dwordx4 v[218:219], off
	v_lshl_add_u64 v[218:219], s[74:75], 0, v[130:131]
	s_mov_b32 m0, s7
	s_nop 0
	global_load_lds_dwordx4 v[218:219], off
	s_mov_b32 m0, s9
	s_nop 0
	global_load_lds_dwordx4 v[220:221], off
	s_waitcnt vmcnt(8)
	s_waitcnt lgkmcnt(0)
	s_barrier
	s_setprio 1
	s_waitcnt lgkmcnt(0)
	v_mfma_f32_16x16x32_bf16 v[94:97], v[150:153], v[182:185], v[94:97]
	v_mfma_f32_16x16x32_bf16 v[90:93], v[158:161], v[182:185], v[90:93]
	v_mfma_f32_16x16x32_bf16 v[86:89], v[150:153], v[190:193], v[86:89]
	v_mfma_f32_16x16x32_bf16 v[82:85], v[158:161], v[190:193], v[82:85]
	v_mfma_f32_16x16x32_bf16 v[78:81], v[150:153], v[198:201], v[78:81]
	v_mfma_f32_16x16x32_bf16 v[74:77], v[158:161], v[198:201], v[74:77]
	v_mfma_f32_16x16x32_bf16 v[70:73], v[150:153], v[206:209], v[70:73]
	v_mfma_f32_16x16x32_bf16 v[66:69], v[158:161], v[206:209], v[66:69]
	v_mfma_f32_16x16x32_bf16 v[94:97], v[154:157], v[186:189], v[94:97]
	v_mfma_f32_16x16x32_bf16 v[90:93], v[162:165], v[186:189], v[90:93]
	v_mfma_f32_16x16x32_bf16 v[86:89], v[154:157], v[194:197], v[86:89]
	v_mfma_f32_16x16x32_bf16 v[82:85], v[162:165], v[194:197], v[82:85]
	v_mfma_f32_16x16x32_bf16 v[78:81], v[154:157], v[202:205], v[78:81]
	v_mfma_f32_16x16x32_bf16 v[74:77], v[162:165], v[202:205], v[74:77]
	v_mfma_f32_16x16x32_bf16 v[70:73], v[154:157], v[210:213], v[70:73]
	v_mfma_f32_16x16x32_bf16 v[66:69], v[162:165], v[210:213], v[66:69]
	s_setprio 0
	s_setprio 1
	v_mfma_f32_16x16x32_bf16 v[30:33], v[166:169], v[182:185], v[30:33]
	v_mfma_f32_16x16x32_bf16 v[26:29], v[174:177], v[182:185], v[26:29]
	v_mfma_f32_16x16x32_bf16 v[22:25], v[166:169], v[190:193], v[22:25]
	v_mfma_f32_16x16x32_bf16 v[18:21], v[174:177], v[190:193], v[18:21]
	v_mfma_f32_16x16x32_bf16 v[14:17], v[166:169], v[198:201], v[14:17]
	v_mfma_f32_16x16x32_bf16 v[10:13], v[174:177], v[198:201], v[10:13]
	v_mfma_f32_16x16x32_bf16 v[6:9], v[166:169], v[206:209], v[6:9]
	v_mfma_f32_16x16x32_bf16 v[0:3], v[174:177], v[206:209], v[0:3]
	v_mfma_f32_16x16x32_bf16 v[30:33], v[170:173], v[186:189], v[30:33]
	v_mfma_f32_16x16x32_bf16 v[26:29], v[178:181], v[186:189], v[26:29]
	v_mfma_f32_16x16x32_bf16 v[22:25], v[170:173], v[194:197], v[22:25]
	v_mfma_f32_16x16x32_bf16 v[18:21], v[178:181], v[194:197], v[18:21]
	v_mfma_f32_16x16x32_bf16 v[14:17], v[170:173], v[202:205], v[14:17]
	v_mfma_f32_16x16x32_bf16 v[10:13], v[178:181], v[202:205], v[10:13]
	v_mfma_f32_16x16x32_bf16 v[6:9], v[170:173], v[210:213], v[6:9]
	v_mfma_f32_16x16x32_bf16 v[0:3], v[178:181], v[210:213], v[0:3]
	s_setprio 0
	s_barrier
	s_add_i32 s86, 32, 0x18000
	s_add_i32 s87, 32, 0x1c000
	v_add_u32_e32 v162, s86, v148
	v_add_u32_e32 v178, s87, v148
	ds_read_b128 v[150:153], v162
	ds_read_b128 v[154:157], v162 offset:1024
	ds_read_b128 v[158:161], v162 offset:2048
	ds_read_b128 v[162:165], v162 offset:3072
	ds_read_b128 v[166:169], v178
	ds_read_b128 v[170:173], v178 offset:1024
	ds_read_b128 v[174:177], v178 offset:2048
	ds_read_b128 v[178:181], v178 offset:3072
	s_add_u32 s74, s74, 0x40000
	s_addc_u32 s75, s75, 0
	s_mov_b32 m0, s17
	v_lshl_add_u64 v[222:223], s[74:75], 0, v[130:131]
	ds_read_b128 v[182:185], v149 offset:32768
	ds_read_b128 v[186:189], v149 offset:33792
	ds_read_b128 v[190:193], v149 offset:34816
	ds_read_b128 v[194:197], v149 offset:35840
	ds_read_b128 v[198:201], v149 offset:36864
	ds_read_b128 v[202:205], v149 offset:37888
	ds_read_b128 v[206:209], v149 offset:38912
	ds_read_b128 v[210:213], v149 offset:39936
	global_load_lds_dwordx4 v[222:223], off
	v_lshl_add_u64 v[222:223], s[74:75], 0, v[134:135]
	s_mov_b32 m0, s18
	s_nop 0
	global_load_lds_dwordx4 v[222:223], off
	s_waitcnt vmcnt(8)
	s_waitcnt lgkmcnt(0)
	s_barrier
	s_setprio 1
	s_waitcnt lgkmcnt(0)
	v_mfma_f32_16x16x32_bf16 v[126:129], v[150:153], v[182:185], v[126:129]
	v_mfma_f32_16x16x32_bf16 v[122:125], v[158:161], v[182:185], v[122:125]
	v_mfma_f32_16x16x32_bf16 v[118:121], v[150:153], v[190:193], v[118:121]
	v_mfma_f32_16x16x32_bf16 v[114:117], v[158:161], v[190:193], v[114:117]
	v_mfma_f32_16x16x32_bf16 v[110:113], v[150:153], v[198:201], v[110:113]
	v_mfma_f32_16x16x32_bf16 v[106:109], v[158:161], v[198:201], v[106:109]
	v_mfma_f32_16x16x32_bf16 v[102:105], v[150:153], v[206:209], v[102:105]
	v_mfma_f32_16x16x32_bf16 v[98:101], v[158:161], v[206:209], v[98:101]
	v_mfma_f32_16x16x32_bf16 v[126:129], v[154:157], v[186:189], v[126:129]
	v_mfma_f32_16x16x32_bf16 v[122:125], v[162:165], v[186:189], v[122:125]
	v_mfma_f32_16x16x32_bf16 v[118:121], v[154:157], v[194:197], v[118:121]
	v_mfma_f32_16x16x32_bf16 v[114:117], v[162:165], v[194:197], v[114:117]
	v_mfma_f32_16x16x32_bf16 v[110:113], v[154:157], v[202:205], v[110:113]
	v_mfma_f32_16x16x32_bf16 v[106:109], v[162:165], v[202:205], v[106:109]
	v_mfma_f32_16x16x32_bf16 v[102:105], v[154:157], v[210:213], v[102:105]
	v_mfma_f32_16x16x32_bf16 v[98:101], v[162:165], v[210:213], v[98:101]
	s_setprio 0
	s_setprio 1
	v_mfma_f32_16x16x32_bf16 v[62:65], v[166:169], v[182:185], v[62:65]
	v_mfma_f32_16x16x32_bf16 v[58:61], v[174:177], v[182:185], v[58:61]
	v_mfma_f32_16x16x32_bf16 v[54:57], v[166:169], v[190:193], v[54:57]
	v_mfma_f32_16x16x32_bf16 v[50:53], v[174:177], v[190:193], v[50:53]
	v_mfma_f32_16x16x32_bf16 v[46:49], v[166:169], v[198:201], v[46:49]
	v_mfma_f32_16x16x32_bf16 v[42:45], v[174:177], v[198:201], v[42:45]
	v_mfma_f32_16x16x32_bf16 v[38:41], v[166:169], v[206:209], v[38:41]
	v_mfma_f32_16x16x32_bf16 v[34:37], v[174:177], v[206:209], v[34:37]
	v_mfma_f32_16x16x32_bf16 v[62:65], v[170:173], v[186:189], v[62:65]
	v_mfma_f32_16x16x32_bf16 v[58:61], v[178:181], v[186:189], v[58:61]
	v_mfma_f32_16x16x32_bf16 v[54:57], v[170:173], v[194:197], v[54:57]
	v_mfma_f32_16x16x32_bf16 v[50:53], v[178:181], v[194:197], v[50:53]
	v_mfma_f32_16x16x32_bf16 v[46:49], v[170:173], v[202:205], v[46:49]
	v_mfma_f32_16x16x32_bf16 v[42:45], v[178:181], v[202:205], v[42:45]
	v_mfma_f32_16x16x32_bf16 v[38:41], v[170:173], v[210:213], v[38:41]
	v_mfma_f32_16x16x32_bf16 v[34:37], v[178:181], v[210:213], v[34:37]
	s_setprio 0
	s_barrier
	s_add_i32 s74, s86, s16
	v_lshl_add_u64 v[214:215], v[214:215], 0, s[54:55]
	s_mov_b32 m0, s74
	ds_read_b128 v[182:185], v149 offset:49152
	ds_read_b128 v[186:189], v149 offset:50176
	ds_read_b128 v[190:193], v149 offset:51200
	ds_read_b128 v[194:197], v149 offset:52224
	ds_read_b128 v[198:201], v149 offset:53248
	ds_read_b128 v[202:205], v149 offset:54272
	ds_read_b128 v[206:209], v149 offset:55296
	ds_read_b128 v[210:213], v149 offset:56320
	global_load_lds_dwordx4 v[214:215], off
	s_add_i32 m0, s74, 0x2000
	s_add_u32 s72, s72, 0x40080
	v_lshl_add_u64 v[214:215], v[216:217], 0, s[54:55]
	s_addc_u32 s73, s73, 0
	s_add_i32 s74, s87, s16
	global_load_lds_dwordx4 v[214:215], off
	v_lshl_add_u64 v[214:215], s[72:73], 0, v[132:133]
	s_mov_b32 m0, s74
	s_nop 0
	global_load_lds_dwordx4 v[214:215], off
	v_lshl_add_u64 v[214:215], s[72:73], 0, v[136:137]
	s_add_i32 m0, s74, 0x2000
	s_nop 0
	global_load_lds_dwordx4 v[214:215], off
	v_lshl_add_u64 v[214:215], v[218:219], 0, s[54:55]
	s_mov_b32 m0, s44
	s_nop 0
	global_load_lds_dwordx4 v[214:215], off
	v_lshl_add_u64 v[214:215], v[220:221], 0, s[54:55]
	s_mov_b32 m0, s45
	s_nop 0
	global_load_lds_dwordx4 v[214:215], off
	s_waitcnt vmcnt(8)
	s_waitcnt lgkmcnt(0)
	s_barrier
	s_setprio 1
	s_waitcnt lgkmcnt(0)
	v_mfma_f32_16x16x32_bf16 v[94:97], v[150:153], v[182:185], v[94:97]
	v_mfma_f32_16x16x32_bf16 v[90:93], v[158:161], v[182:185], v[90:93]
	v_mfma_f32_16x16x32_bf16 v[86:89], v[150:153], v[190:193], v[86:89]
	v_mfma_f32_16x16x32_bf16 v[82:85], v[158:161], v[190:193], v[82:85]
	v_mfma_f32_16x16x32_bf16 v[78:81], v[150:153], v[198:201], v[78:81]
	v_mfma_f32_16x16x32_bf16 v[74:77], v[158:161], v[198:201], v[74:77]
	v_mfma_f32_16x16x32_bf16 v[70:73], v[150:153], v[206:209], v[70:73]
	v_mfma_f32_16x16x32_bf16 v[66:69], v[158:161], v[206:209], v[66:69]
	v_mfma_f32_16x16x32_bf16 v[94:97], v[154:157], v[186:189], v[94:97]
	v_mfma_f32_16x16x32_bf16 v[90:93], v[162:165], v[186:189], v[90:93]
	v_mfma_f32_16x16x32_bf16 v[86:89], v[154:157], v[194:197], v[86:89]
	v_mfma_f32_16x16x32_bf16 v[82:85], v[162:165], v[194:197], v[82:85]
	v_mfma_f32_16x16x32_bf16 v[78:81], v[154:157], v[202:205], v[78:81]
	v_mfma_f32_16x16x32_bf16 v[74:77], v[162:165], v[202:205], v[74:77]
	v_mfma_f32_16x16x32_bf16 v[70:73], v[154:157], v[210:213], v[70:73]
	v_mfma_f32_16x16x32_bf16 v[66:69], v[162:165], v[210:213], v[66:69]
	s_setprio 0
	s_setprio 1
	v_mfma_f32_16x16x32_bf16 v[30:33], v[166:169], v[182:185], v[30:33]
	v_mfma_f32_16x16x32_bf16 v[26:29], v[174:177], v[182:185], v[26:29]
	v_mfma_f32_16x16x32_bf16 v[22:25], v[166:169], v[190:193], v[22:25]
	v_mfma_f32_16x16x32_bf16 v[18:21], v[174:177], v[190:193], v[18:21]
	v_mfma_f32_16x16x32_bf16 v[14:17], v[166:169], v[198:201], v[14:17]
	v_mfma_f32_16x16x32_bf16 v[10:13], v[174:177], v[198:201], v[10:13]
	v_mfma_f32_16x16x32_bf16 v[6:9], v[166:169], v[206:209], v[6:9]
	v_mfma_f32_16x16x32_bf16 v[0:3], v[174:177], v[206:209], v[0:3]
	v_mfma_f32_16x16x32_bf16 v[30:33], v[170:173], v[186:189], v[30:33]
	v_mfma_f32_16x16x32_bf16 v[26:29], v[178:181], v[186:189], v[26:29]
	v_mfma_f32_16x16x32_bf16 v[22:25], v[170:173], v[194:197], v[22:25]
	v_mfma_f32_16x16x32_bf16 v[18:21], v[178:181], v[194:197], v[18:21]
	v_mfma_f32_16x16x32_bf16 v[14:17], v[170:173], v[202:205], v[14:17]
	v_mfma_f32_16x16x32_bf16 v[10:13], v[178:181], v[202:205], v[10:13]
	v_mfma_f32_16x16x32_bf16 v[6:9], v[170:173], v[210:213], v[6:9]
	v_mfma_f32_16x16x32_bf16 v[0:3], v[178:181], v[210:213], v[0:3]
	s_setprio 0
	s_add_u32 s70, s70, 0x100
	s_addc_u32 s71, s71, 0
	s_add_u32 s83, s83, 0x100
	s_addc_u32 s84, s84, 0
	s_cmp_ge_i32 s85, s35
	s_mov_b32 s72, s85
	s_cbranch_scc1 .Lrotx_2
	s_add_i32 s85, s72, 2
	s_add_u32 s73, s70, 0xfffc0080
	s_addc_u32 s74, s71, -1
	s_add_i32 s86, 32, 0x10000
	s_cmp_eq_u32 s50, s72
	s_cselect_b32 s75, s76, s74
	s_cselect_b32 s74, s77, s73
	s_cselect_b32 s73, s78, s84
	s_cselect_b32 s72, s79, s83
	s_add_i32 s90, 32, 0x14000
	s_barrier
	s_branch .Lrot_2
.Lrotx_2:
	s_barrier
.LBB0_1259:
	s_and_b64 vcc, exec, s[14:15]
	s_cbranch_vccz .LBB0_1261
	s_barrier

.Lrot_3:
	v_add_u32_e32 v162, s86, v160
	v_add_u32_e32 v178, s90, v160
	ds_read_b128 v[130:133], v162
	ds_read_b128 v[134:137], v162 offset:1024
	ds_read_b128 v[156:159], v162 offset:2048
	ds_read_b128 v[162:165], v162 offset:3072
	ds_read_b128 v[166:169], v178
	ds_read_b128 v[170:173], v178 offset:1024
	ds_read_b128 v[174:177], v178 offset:2048
	ds_read_b128 v[178:181], v178 offset:3072
	v_lshl_add_u64 v[214:215], s[4:5], 0, v[152:153]
	s_add_i32 m0, s17, 0xc000
	ds_read_b128 v[182:185], v161
	ds_read_b128 v[186:189], v161 offset:1024
	ds_read_b128 v[190:193], v161 offset:2048
	ds_read_b128 v[194:197], v161 offset:3072
	ds_read_b128 v[198:201], v161 offset:4096
	ds_read_b128 v[202:205], v161 offset:5120
	ds_read_b128 v[206:209], v161 offset:6144
	ds_read_b128 v[210:213], v161 offset:7168
	global_load_lds_dwordx4 v[214:215], off
	v_lshl_add_u64 v[214:215], s[4:5], 0, v[154:155]
	s_add_i32 m0, s17, 0xe000
	s_nop 0
	global_load_lds_dwordx4 v[214:215], off
	s_waitcnt vmcnt(8)
	s_waitcnt lgkmcnt(0)
	s_barrier
	s_setprio 1
	s_waitcnt lgkmcnt(0)
	v_mfma_f32_16x16x32_bf16 v[126:129], v[130:133], v[182:185], v[126:129]
	v_mfma_f32_16x16x32_bf16 v[122:125], v[156:159], v[182:185], v[122:125]
	v_mfma_f32_16x16x32_bf16 v[118:121], v[130:133], v[190:193], v[118:121]
	v_mfma_f32_16x16x32_bf16 v[114:117], v[156:159], v[190:193], v[114:117]
	v_mfma_f32_16x16x32_bf16 v[110:113], v[130:133], v[198:201], v[110:113]
	v_mfma_f32_16x16x32_bf16 v[106:109], v[156:159], v[198:201], v[106:109]
	v_mfma_f32_16x16x32_bf16 v[102:105], v[130:133], v[206:209], v[102:105]
	v_mfma_f32_16x16x32_bf16 v[98:101], v[156:159], v[206:209], v[98:101]
	v_mfma_f32_16x16x32_bf16 v[126:129], v[134:137], v[186:189], v[126:129]
	v_mfma_f32_16x16x32_bf16 v[122:125], v[162:165], v[186:189], v[122:125]
	v_mfma_f32_16x16x32_bf16 v[118:121], v[134:137], v[194:197], v[118:121]
	v_mfma_f32_16x16x32_bf16 v[114:117], v[162:165], v[194:197], v[114:117]
	v_mfma_f32_16x16x32_bf16 v[110:113], v[134:137], v[202:205], v[110:113]
	v_mfma_f32_16x16x32_bf16 v[106:109], v[162:165], v[202:205], v[106:109]
	v_mfma_f32_16x16x32_bf16 v[102:105], v[134:137], v[210:213], v[102:105]
	v_mfma_f32_16x16x32_bf16 v[98:101], v[162:165], v[210:213], v[98:101]
	s_setprio 0
	s_setprio 1
	v_mfma_f32_16x16x32_bf16 v[62:65], v[166:169], v[182:185], v[62:65]
	v_mfma_f32_16x16x32_bf16 v[58:61], v[174:177], v[182:185], v[58:61]
	v_mfma_f32_16x16x32_bf16 v[54:57], v[166:169], v[190:193], v[54:57]
	v_mfma_f32_16x16x32_bf16 v[50:53], v[174:177], v[190:193], v[50:53]
	v_mfma_f32_16x16x32_bf16 v[46:49], v[166:169], v[198:201], v[46:49]
	v_mfma_f32_16x16x32_bf16 v[42:45], v[174:177], v[198:201], v[42:45]
	v_mfma_f32_16x16x32_bf16 v[38:41], v[166:169], v[206:209], v[38:41]
	v_mfma_f32_16x16x32_bf16 v[34:37], v[174:177], v[206:209], v[34:37]
	v_mfma_f32_16x16x32_bf16 v[62:65], v[170:173], v[186:189], v[62:65]
	v_mfma_f32_16x16x32_bf16 v[58:61], v[178:181], v[186:189], v[58:61]
	v_mfma_f32_16x16x32_bf16 v[54:57], v[170:173], v[194:197], v[54:57]
	v_mfma_f32_16x16x32_bf16 v[50:53], v[178:181], v[194:197], v[50:53]
	v_mfma_f32_16x16x32_bf16 v[46:49], v[170:173], v[202:205], v[46:49]
	v_mfma_f32_16x16x32_bf16 v[42:45], v[178:181], v[202:205], v[42:45]
	v_mfma_f32_16x16x32_bf16 v[38:41], v[170:173], v[210:213], v[38:41]
	v_mfma_f32_16x16x32_bf16 v[34:37], v[178:181], v[210:213], v[34:37]
	s_setprio 0
	s_barrier
	s_add_i32 s86, s86, s16
	v_lshl_add_u64 v[214:215], s[70:71], 0, v[146:147]
	s_mov_b32 m0, s86
	ds_read_b128 v[182:185], v161 offset:16384
	ds_read_b128 v[186:189], v161 offset:17408
	ds_read_b128 v[190:193], v161 offset:18432
	ds_read_b128 v[194:197], v161 offset:19456
	ds_read_b128 v[198:201], v161 offset:20480
	ds_read_b128 v[202:205], v161 offset:21504
	ds_read_b128 v[206:209], v161 offset:22528
	ds_read_b128 v[210:213], v161 offset:23552
	global_load_lds_dwordx4 v[214:215], off
	s_add_i32 m0, s86, 0x2000
	s_add_u32 s86, s70, 0x40000
	v_lshl_add_u64 v[216:217], s[70:71], 0, v[150:151]
	s_addc_u32 s87, s71, 0
	s_add_i32 s90, s90, s16
	global_load_lds_dwordx4 v[216:217], off
	v_lshl_add_u64 v[218:219], s[86:87], 0, v[146:147]
	s_mov_b32 m0, s90
	v_lshl_add_u64 v[220:221], s[72:73], 0, v[148:149]
	global_load_lds_dwordx4 v[218:219], off
	v_lshl_add_u64 v[218:219], s[86:87], 0, v[150:151]
	s_add_i32 m0, s90, 0x2000
	s_nop 0
	global_load_lds_dwordx4 v[218:219], off
	v_lshl_add_u64 v[218:219], s[72:73], 0, v[144:145]
	s_mov_b32 m0, s17
	s_nop 0
	global_load_lds_dwordx4 v[218:219], off
	s_mov_b32 m0, s18
	s_nop 0
	global_load_lds_dwordx4 v[220:221], off
	s_waitcnt vmcnt(8)
	s_waitcnt lgkmcnt(0)
	s_barrier
	s_setprio 1
	s_waitcnt lgkmcnt(0)
	v_mfma_f32_16x16x32_bf16 v[94:97], v[130:133], v[182:185], v[94:97]
	v_mfma_f32_16x16x32_bf16 v[90:93], v[156:159], v[182:185], v[90:93]
	v_mfma_f32_16x16x32_bf16 v[86:89], v[130:133], v[190:193], v[86:89]
	v_mfma_f32_16x16x32_bf16 v[82:85], v[156:159], v[190:193], v[82:85]
	v_mfma_f32_16x16x32_bf16 v[78:81], v[130:133], v[198:201], v[78:81]
	v_mfma_f32_16x16x32_bf16 v[74:77], v[156:159], v[198:201], v[74:77]
	v_mfma_f32_16x16x32_bf16 v[70:73], v[130:133], v[206:209], v[70:73]
	v_mfma_f32_16x16x32_bf16 v[66:69], v[156:159], v[206:209], v[66:69]
	v_mfma_f32_16x16x32_bf16 v[94:97], v[134:137], v[186:189], v[94:97]
	v_mfma_f32_16x16x32_bf16 v[90:93], v[162:165], v[186:189], v[90:93]
	v_mfma_f32_16x16x32_bf16 v[86:89], v[134:137], v[194:197], v[86:89]
	v_mfma_f32_16x16x32_bf16 v[82:85], v[162:165], v[194:197], v[82:85]
	v_mfma_f32_16x16x32_bf16 v[78:81], v[134:137], v[202:205], v[78:81]
	v_mfma_f32_16x16x32_bf16 v[74:77], v[162:165], v[202:205], v[74:77]
	v_mfma_f32_16x16x32_bf16 v[70:73], v[134:137], v[210:213], v[70:73]
	v_mfma_f32_16x16x32_bf16 v[66:69], v[162:165], v[210:213], v[66:69]
	s_setprio 0
	s_setprio 1
	v_mfma_f32_16x16x32_bf16 v[30:33], v[166:169], v[182:185], v[30:33]
	v_mfma_f32_16x16x32_bf16 v[26:29], v[174:177], v[182:185], v[26:29]
	v_mfma_f32_16x16x32_bf16 v[22:25], v[166:169], v[190:193], v[22:25]
	v_mfma_f32_16x16x32_bf16 v[18:21], v[174:177], v[190:193], v[18:21]
	v_mfma_f32_16x16x32_bf16 v[14:17], v[166:169], v[198:201], v[14:17]
	v_mfma_f32_16x16x32_bf16 v[10:13], v[174:177], v[198:201], v[10:13]
	v_mfma_f32_16x16x32_bf16 v[6:9], v[166:169], v[206:209], v[6:9]
	v_mfma_f32_16x16x32_bf16 v[0:3], v[174:177], v[206:209], v[0:3]
	v_mfma_f32_16x16x32_bf16 v[30:33], v[170:173], v[186:189], v[30:33]
	v_mfma_f32_16x16x32_bf16 v[26:29], v[178:181], v[186:189], v[26:29]
	v_mfma_f32_16x16x32_bf16 v[22:25], v[170:173], v[194:197], v[22:25]
	v_mfma_f32_16x16x32_bf16 v[18:21], v[178:181], v[194:197], v[18:21]
	v_mfma_f32_16x16x32_bf16 v[14:17], v[170:173], v[202:205], v[14:17]
	v_mfma_f32_16x16x32_bf16 v[10:13], v[178:181], v[202:205], v[10:13]
	v_mfma_f32_16x16x32_bf16 v[6:9], v[170:173], v[210:213], v[6:9]
	v_mfma_f32_16x16x32_bf16 v[0:3], v[178:181], v[210:213], v[0:3]
	s_setprio 0
	s_barrier
	s_add_i32 s86, 32, 0x18000
	s_add_i32 s87, 32, 0x1c000
	v_add_u32_e32 v162, s86, v160
	v_add_u32_e32 v178, s87, v160
	ds_read_b128 v[130:133], v162
	ds_read_b128 v[134:137], v162 offset:1024
	ds_read_b128 v[156:159], v162 offset:2048
	ds_read_b128 v[162:165], v162 offset:3072
	ds_read_b128 v[166:169], v178
	ds_read_b128 v[170:173], v178 offset:1024
	ds_read_b128 v[174:177], v178 offset:2048
	ds_read_b128 v[178:181], v178 offset:3072
	s_add_u32 s72, s72, 0x40000
	s_addc_u32 s73, s73, 0
	s_mov_b32 m0, s35
	v_lshl_add_u64 v[222:223], s[72:73], 0, v[144:145]
	ds_read_b128 v[182:185], v161 offset:32768
	ds_read_b128 v[186:189], v161 offset:33792
	ds_read_b128 v[190:193], v161 offset:34816
	ds_read_b128 v[194:197], v161 offset:35840
	ds_read_b128 v[198:201], v161 offset:36864
	ds_read_b128 v[202:205], v161 offset:37888
	ds_read_b128 v[206:209], v161 offset:38912
	ds_read_b128 v[210:213], v161 offset:39936
	global_load_lds_dwordx4 v[222:223], off
	v_lshl_add_u64 v[222:223], s[72:73], 0, v[148:149]
	s_mov_b32 m0, s44
	s_nop 0
	global_load_lds_dwordx4 v[222:223], off
	s_waitcnt vmcnt(8)
	s_waitcnt lgkmcnt(0)
	s_barrier
	s_setprio 1
	s_waitcnt lgkmcnt(0)
	v_mfma_f32_16x16x32_bf16 v[126:129], v[130:133], v[182:185], v[126:129]
	v_mfma_f32_16x16x32_bf16 v[122:125], v[156:159], v[182:185], v[122:125]
	v_mfma_f32_16x16x32_bf16 v[118:121], v[130:133], v[190:193], v[118:121]
	v_mfma_f32_16x16x32_bf16 v[114:117], v[156:159], v[190:193], v[114:117]
	v_mfma_f32_16x16x32_bf16 v[110:113], v[130:133], v[198:201], v[110:113]
	v_mfma_f32_16x16x32_bf16 v[106:109], v[156:159], v[198:201], v[106:109]
	v_mfma_f32_16x16x32_bf16 v[102:105], v[130:133], v[206:209], v[102:105]
	v_mfma_f32_16x16x32_bf16 v[98:101], v[156:159], v[206:209], v[98:101]
	v_mfma_f32_16x16x32_bf16 v[126:129], v[134:137], v[186:189], v[126:129]
	v_mfma_f32_16x16x32_bf16 v[122:125], v[162:165], v[186:189], v[122:125]
	v_mfma_f32_16x16x32_bf16 v[118:121], v[134:137], v[194:197], v[118:121]
	v_mfma_f32_16x16x32_bf16 v[114:117], v[162:165], v[194:197], v[114:117]
	v_mfma_f32_16x16x32_bf16 v[110:113], v[134:137], v[202:205], v[110:113]
	v_mfma_f32_16x16x32_bf16 v[106:109], v[162:165], v[202:205], v[106:109]
	v_mfma_f32_16x16x32_bf16 v[102:105], v[134:137], v[210:213], v[102:105]
	v_mfma_f32_16x16x32_bf16 v[98:101], v[162:165], v[210:213], v[98:101]
	s_setprio 0
	s_setprio 1
	v_mfma_f32_16x16x32_bf16 v[62:65], v[166:169], v[182:185], v[62:65]
	v_mfma_f32_16x16x32_bf16 v[58:61], v[174:177], v[182:185], v[58:61]
	v_mfma_f32_16x16x32_bf16 v[54:57], v[166:169], v[190:193], v[54:57]
	v_mfma_f32_16x16x32_bf16 v[50:53], v[174:177], v[190:193], v[50:53]
	v_mfma_f32_16x16x32_bf16 v[46:49], v[166:169], v[198:201], v[46:49]
	v_mfma_f32_16x16x32_bf16 v[42:45], v[174:177], v[198:201], v[42:45]
	v_mfma_f32_16x16x32_bf16 v[38:41], v[166:169], v[206:209], v[38:41]
	v_mfma_f32_16x16x32_bf16 v[34:37], v[174:177], v[206:209], v[34:37]
	v_mfma_f32_16x16x32_bf16 v[62:65], v[170:173], v[186:189], v[62:65]
	v_mfma_f32_16x16x32_bf16 v[58:61], v[178:181], v[186:189], v[58:61]
	v_mfma_f32_16x16x32_bf16 v[54:57], v[170:173], v[194:197], v[54:57]
	v_mfma_f32_16x16x32_bf16 v[50:53], v[178:181], v[194:197], v[50:53]
	v_mfma_f32_16x16x32_bf16 v[46:49], v[170:173], v[202:205], v[46:49]
	v_mfma_f32_16x16x32_bf16 v[42:45], v[178:181], v[202:205], v[42:45]
	v_mfma_f32_16x16x32_bf16 v[38:41], v[170:173], v[210:213], v[38:41]
	v_mfma_f32_16x16x32_bf16 v[34:37], v[178:181], v[210:213], v[34:37]
	s_setprio 0
	s_barrier
	s_add_i32 s72, s86, s16
	v_lshl_add_u64 v[214:215], v[214:215], 0, s[54:55]
	s_mov_b32 m0, s72
	ds_read_b128 v[182:185], v161 offset:49152
	ds_read_b128 v[186:189], v161 offset:50176
	ds_read_b128 v[190:193], v161 offset:51200
	ds_read_b128 v[194:197], v161 offset:52224
	ds_read_b128 v[198:201], v161 offset:53248
	ds_read_b128 v[202:205], v161 offset:54272
	ds_read_b128 v[206:209], v161 offset:55296
	ds_read_b128 v[210:213], v161 offset:56320
	global_load_lds_dwordx4 v[214:215], off
	s_add_i32 m0, s72, 0x2000
	s_add_u32 s70, s70, 0x40080
	v_lshl_add_u64 v[214:215], v[216:217], 0, s[54:55]
	s_addc_u32 s71, s71, 0
	s_add_i32 s72, s87, s16
	global_load_lds_dwordx4 v[214:215], off
	v_lshl_add_u64 v[214:215], s[70:71], 0, v[146:147]
	s_mov_b32 m0, s72
	s_nop 0
	global_load_lds_dwordx4 v[214:215], off
	v_lshl_add_u64 v[214:215], s[70:71], 0, v[150:151]
	s_add_i32 m0, s72, 0x2000
	s_nop 0
	global_load_lds_dwordx4 v[214:215], off
	v_lshl_add_u64 v[214:215], v[218:219], 0, s[54:55]
	s_mov_b32 m0, s56
	s_nop 0
	global_load_lds_dwordx4 v[214:215], off
	v_lshl_add_u64 v[214:215], v[220:221], 0, s[54:55]
	s_mov_b32 m0, s57
	s_nop 0
	global_load_lds_dwordx4 v[214:215], off
	s_waitcnt vmcnt(8)
	s_waitcnt lgkmcnt(0)
	s_barrier
	s_setprio 1
	s_waitcnt lgkmcnt(0)
	v_mfma_f32_16x16x32_bf16 v[94:97], v[130:133], v[182:185], v[94:97]
	v_mfma_f32_16x16x32_bf16 v[90:93], v[156:159], v[182:185], v[90:93]
	v_mfma_f32_16x16x32_bf16 v[86:89], v[130:133], v[190:193], v[86:89]
	v_mfma_f32_16x16x32_bf16 v[82:85], v[156:159], v[190:193], v[82:85]
	v_mfma_f32_16x16x32_bf16 v[78:81], v[130:133], v[198:201], v[78:81]
	v_mfma_f32_16x16x32_bf16 v[74:77], v[156:159], v[198:201], v[74:77]
	v_mfma_f32_16x16x32_bf16 v[70:73], v[130:133], v[206:209], v[70:73]
	v_mfma_f32_16x16x32_bf16 v[66:69], v[156:159], v[206:209], v[66:69]
	v_mfma_f32_16x16x32_bf16 v[94:97], v[134:137], v[186:189], v[94:97]
	v_mfma_f32_16x16x32_bf16 v[90:93], v[162:165], v[186:189], v[90:93]
	v_mfma_f32_16x16x32_bf16 v[86:89], v[134:137], v[194:197], v[86:89]
	v_mfma_f32_16x16x32_bf16 v[82:85], v[162:165], v[194:197], v[82:85]
	v_mfma_f32_16x16x32_bf16 v[78:81], v[134:137], v[202:205], v[78:81]
	v_mfma_f32_16x16x32_bf16 v[74:77], v[162:165], v[202:205], v[74:77]
	v_mfma_f32_16x16x32_bf16 v[70:73], v[134:137], v[210:213], v[70:73]
	v_mfma_f32_16x16x32_bf16 v[66:69], v[162:165], v[210:213], v[66:69]
	s_setprio 0
	s_setprio 1
	v_mfma_f32_16x16x32_bf16 v[30:33], v[166:169], v[182:185], v[30:33]
	v_mfma_f32_16x16x32_bf16 v[26:29], v[174:177], v[182:185], v[26:29]
	v_mfma_f32_16x16x32_bf16 v[22:25], v[166:169], v[190:193], v[22:25]
	v_mfma_f32_16x16x32_bf16 v[18:21], v[174:177], v[190:193], v[18:21]
	v_mfma_f32_16x16x32_bf16 v[14:17], v[166:169], v[198:201], v[14:17]
	v_mfma_f32_16x16x32_bf16 v[10:13], v[174:177], v[198:201], v[10:13]
	v_mfma_f32_16x16x32_bf16 v[6:9], v[166:169], v[206:209], v[6:9]
	v_mfma_f32_16x16x32_bf16 v[0:3], v[174:177], v[206:209], v[0:3]
	v_mfma_f32_16x16x32_bf16 v[30:33], v[170:173], v[186:189], v[30:33]
	v_mfma_f32_16x16x32_bf16 v[26:29], v[178:181], v[186:189], v[26:29]
	v_mfma_f32_16x16x32_bf16 v[22:25], v[170:173], v[194:197], v[22:25]
	v_mfma_f32_16x16x32_bf16 v[18:21], v[178:181], v[194:197], v[18:21]
	v_mfma_f32_16x16x32_bf16 v[14:17], v[170:173], v[202:205], v[14:17]
	v_mfma_f32_16x16x32_bf16 v[10:13], v[178:181], v[202:205], v[10:13]
	v_mfma_f32_16x16x32_bf16 v[6:9], v[170:173], v[210:213], v[6:9]
	v_mfma_f32_16x16x32_bf16 v[0:3], v[178:181], v[210:213], v[0:3]
	s_setprio 0
	s_add_u32 s4, s4, 0x100
	s_addc_u32 s5, s5, 0
	s_add_u32 s79, s79, 0x100
	s_addc_u32 s84, s84, 0
	s_cmp_ge_u32 s85, s50
	s_mov_b32 s70, s85
	s_cbranch_scc1 .Lrotx_3
	s_add_i32 s85, s70, 2
	s_add_u32 s71, s4, 0xfffc0080
	s_addc_u32 s72, s5, -1
	s_add_i32 s86, 32, 0x10000
	s_cmp_eq_u32 s78, s70
	s_cselect_b32 s73, s74, s72
	s_cselect_b32 s72, s75, s71
	s_cselect_b32 s71, s76, s84
	s_cselect_b32 s70, s77, s79
	s_add_i32 s90, 32, 0x14000
	s_barrier
	s_branch .Lrot_3
.Lrotx_3:
	s_barrier
	s_and_b64 vcc, exec, s[14:15]
	s_cbranch_vccz .LBB0_1278

.Lrot_4:
	v_add_u32_e32 v160, s19, v180
	v_add_u32_e32 v176, s22, v180
	ds_read_b128 v[130:133], v160
	ds_read_b128 v[134:137], v160 offset:1024
	ds_read_b128 v[156:159], v160 offset:2048
	ds_read_b128 v[160:163], v160 offset:3072
	ds_read_b128 v[164:167], v176
	ds_read_b128 v[168:171], v176 offset:1024
	ds_read_b128 v[172:175], v176 offset:2048
	ds_read_b128 v[176:179], v176 offset:3072
	v_lshl_add_u64 v[214:215], s[0:1], 0, v[152:153]
	s_add_i32 m0, s68, 0xc000
	ds_read_b128 v[182:185], v181
	ds_read_b128 v[186:189], v181 offset:1024
	ds_read_b128 v[190:193], v181 offset:2048
	ds_read_b128 v[194:197], v181 offset:3072
	ds_read_b128 v[198:201], v181 offset:4096
	ds_read_b128 v[202:205], v181 offset:5120
	ds_read_b128 v[206:209], v181 offset:6144
	ds_read_b128 v[210:213], v181 offset:7168
	global_load_lds_dwordx4 v[214:215], off
	v_lshl_add_u64 v[214:215], s[0:1], 0, v[154:155]
	s_add_i32 m0, s68, 0xe000
	s_nop 0
	global_load_lds_dwordx4 v[214:215], off
	s_waitcnt vmcnt(8)
	s_waitcnt lgkmcnt(0)
	s_barrier
	s_setprio 1
	s_waitcnt lgkmcnt(0)
	v_mfma_f32_16x16x32_bf16 v[126:129], v[130:133], v[182:185], v[126:129]
	v_mfma_f32_16x16x32_bf16 v[122:125], v[156:159], v[182:185], v[122:125]
	v_mfma_f32_16x16x32_bf16 v[118:121], v[130:133], v[190:193], v[118:121]
	v_mfma_f32_16x16x32_bf16 v[114:117], v[156:159], v[190:193], v[114:117]
	v_mfma_f32_16x16x32_bf16 v[110:113], v[130:133], v[198:201], v[110:113]
	v_mfma_f32_16x16x32_bf16 v[106:109], v[156:159], v[198:201], v[106:109]
	v_mfma_f32_16x16x32_bf16 v[102:105], v[130:133], v[206:209], v[102:105]
	v_mfma_f32_16x16x32_bf16 v[98:101], v[156:159], v[206:209], v[98:101]
	v_mfma_f32_16x16x32_bf16 v[126:129], v[134:137], v[186:189], v[126:129]
	v_mfma_f32_16x16x32_bf16 v[122:125], v[160:163], v[186:189], v[122:125]
	v_mfma_f32_16x16x32_bf16 v[118:121], v[134:137], v[194:197], v[118:121]
	v_mfma_f32_16x16x32_bf16 v[114:117], v[160:163], v[194:197], v[114:117]
	v_mfma_f32_16x16x32_bf16 v[110:113], v[134:137], v[202:205], v[110:113]
	v_mfma_f32_16x16x32_bf16 v[106:109], v[160:163], v[202:205], v[106:109]
	v_mfma_f32_16x16x32_bf16 v[102:105], v[134:137], v[210:213], v[102:105]
	v_mfma_f32_16x16x32_bf16 v[98:101], v[160:163], v[210:213], v[98:101]
	s_setprio 0
	s_setprio 1
	v_mfma_f32_16x16x32_bf16 v[62:65], v[164:167], v[182:185], v[62:65]
	v_mfma_f32_16x16x32_bf16 v[58:61], v[172:175], v[182:185], v[58:61]
	v_mfma_f32_16x16x32_bf16 v[54:57], v[164:167], v[190:193], v[54:57]
	v_mfma_f32_16x16x32_bf16 v[50:53], v[172:175], v[190:193], v[50:53]
	v_mfma_f32_16x16x32_bf16 v[46:49], v[164:167], v[198:201], v[46:49]
	v_mfma_f32_16x16x32_bf16 v[42:45], v[172:175], v[198:201], v[42:45]
	v_mfma_f32_16x16x32_bf16 v[38:41], v[164:167], v[206:209], v[38:41]
	v_mfma_f32_16x16x32_bf16 v[34:37], v[172:175], v[206:209], v[34:37]
	v_mfma_f32_16x16x32_bf16 v[62:65], v[168:171], v[186:189], v[62:65]
	v_mfma_f32_16x16x32_bf16 v[58:61], v[176:179], v[186:189], v[58:61]
	v_mfma_f32_16x16x32_bf16 v[54:57], v[168:171], v[194:197], v[54:57]
	v_mfma_f32_16x16x32_bf16 v[50:53], v[176:179], v[194:197], v[50:53]
	v_mfma_f32_16x16x32_bf16 v[46:49], v[168:171], v[202:205], v[46:49]
	v_mfma_f32_16x16x32_bf16 v[42:45], v[176:179], v[202:205], v[42:45]
	v_mfma_f32_16x16x32_bf16 v[38:41], v[168:171], v[210:213], v[38:41]
	v_mfma_f32_16x16x32_bf16 v[34:37], v[176:179], v[210:213], v[34:37]
	s_setprio 0
	s_barrier
	s_add_i32 s19, s19, s51
	v_lshl_add_u64 v[214:215], s[6:7], 0, v[148:149]
	s_mov_b32 m0, s19
	ds_read_b128 v[182:185], v181 offset:16384
	ds_read_b128 v[186:189], v181 offset:17408
	ds_read_b128 v[190:193], v181 offset:18432
	ds_read_b128 v[194:197], v181 offset:19456
	ds_read_b128 v[198:201], v181 offset:20480
	ds_read_b128 v[202:205], v181 offset:21504
	ds_read_b128 v[206:209], v181 offset:22528
	ds_read_b128 v[210:213], v181 offset:23552
	global_load_lds_dwordx4 v[214:215], off
	s_add_i32 m0, s19, 0x2000
	s_add_u32 s20, s6, 0x40000
	v_lshl_add_u64 v[216:217], s[6:7], 0, v[144:145]
	s_addc_u32 s21, s7, 0
	s_add_i32 s19, s22, s51
	global_load_lds_dwordx4 v[216:217], off
	v_lshl_add_u64 v[218:219], s[20:21], 0, v[148:149]
	s_mov_b32 m0, s19
	v_lshl_add_u64 v[220:221], s[8:9], 0, v[146:147]
	global_load_lds_dwordx4 v[218:219], off
	v_lshl_add_u64 v[218:219], s[20:21], 0, v[144:145]
	s_add_i32 m0, s19, 0x2000
	s_nop 0
	global_load_lds_dwordx4 v[218:219], off
	v_lshl_add_u64 v[218:219], s[8:9], 0, v[150:151]
	s_mov_b32 m0, s68
	s_nop 0
	global_load_lds_dwordx4 v[218:219], off
	s_mov_b32 m0, s94
	s_nop 0
	global_load_lds_dwordx4 v[220:221], off
	s_waitcnt vmcnt(8)
	s_waitcnt lgkmcnt(0)
	s_barrier
	s_setprio 1
	s_waitcnt lgkmcnt(0)
	v_mfma_f32_16x16x32_bf16 v[94:97], v[130:133], v[182:185], v[94:97]
	v_mfma_f32_16x16x32_bf16 v[90:93], v[156:159], v[182:185], v[90:93]
	v_mfma_f32_16x16x32_bf16 v[86:89], v[130:133], v[190:193], v[86:89]
	v_mfma_f32_16x16x32_bf16 v[82:85], v[156:159], v[190:193], v[82:85]
	v_mfma_f32_16x16x32_bf16 v[78:81], v[130:133], v[198:201], v[78:81]
	v_mfma_f32_16x16x32_bf16 v[74:77], v[156:159], v[198:201], v[74:77]
	v_mfma_f32_16x16x32_bf16 v[70:73], v[130:133], v[206:209], v[70:73]
	v_mfma_f32_16x16x32_bf16 v[66:69], v[156:159], v[206:209], v[66:69]
	v_mfma_f32_16x16x32_bf16 v[94:97], v[134:137], v[186:189], v[94:97]
	v_mfma_f32_16x16x32_bf16 v[90:93], v[160:163], v[186:189], v[90:93]
	v_mfma_f32_16x16x32_bf16 v[86:89], v[134:137], v[194:197], v[86:89]
	v_mfma_f32_16x16x32_bf16 v[82:85], v[160:163], v[194:197], v[82:85]
	v_mfma_f32_16x16x32_bf16 v[78:81], v[134:137], v[202:205], v[78:81]
	v_mfma_f32_16x16x32_bf16 v[74:77], v[160:163], v[202:205], v[74:77]
	v_mfma_f32_16x16x32_bf16 v[70:73], v[134:137], v[210:213], v[70:73]
	v_mfma_f32_16x16x32_bf16 v[66:69], v[160:163], v[210:213], v[66:69]
	s_setprio 0
	s_setprio 1
	v_mfma_f32_16x16x32_bf16 v[30:33], v[164:167], v[182:185], v[30:33]
	v_mfma_f32_16x16x32_bf16 v[26:29], v[172:175], v[182:185], v[26:29]
	v_mfma_f32_16x16x32_bf16 v[22:25], v[164:167], v[190:193], v[22:25]
	v_mfma_f32_16x16x32_bf16 v[18:21], v[172:175], v[190:193], v[18:21]
	v_mfma_f32_16x16x32_bf16 v[14:17], v[164:167], v[198:201], v[14:17]
	v_mfma_f32_16x16x32_bf16 v[10:13], v[172:175], v[198:201], v[10:13]
	v_mfma_f32_16x16x32_bf16 v[6:9], v[164:167], v[206:209], v[6:9]
	v_mfma_f32_16x16x32_bf16 v[0:3], v[172:175], v[206:209], v[0:3]
	v_mfma_f32_16x16x32_bf16 v[30:33], v[168:171], v[186:189], v[30:33]
	v_mfma_f32_16x16x32_bf16 v[26:29], v[176:179], v[186:189], v[26:29]
	v_mfma_f32_16x16x32_bf16 v[22:25], v[168:171], v[194:197], v[22:25]
	v_mfma_f32_16x16x32_bf16 v[18:21], v[176:179], v[194:197], v[18:21]
	v_mfma_f32_16x16x32_bf16 v[14:17], v[168:171], v[202:205], v[14:17]
	v_mfma_f32_16x16x32_bf16 v[10:13], v[176:179], v[202:205], v[10:13]
	v_mfma_f32_16x16x32_bf16 v[6:9], v[168:171], v[210:213], v[6:9]
	v_mfma_f32_16x16x32_bf16 v[0:3], v[176:179], v[210:213], v[0:3]
	s_setprio 0
	s_barrier
	s_add_i32 s19, 32, 0x18000
	s_add_i32 s20, 32, 0x1c000
	v_add_u32_e32 v160, s19, v180
	v_add_u32_e32 v176, s20, v180
	ds_read_b128 v[130:133], v160
	ds_read_b128 v[134:137], v160 offset:1024
	ds_read_b128 v[156:159], v160 offset:2048
	ds_read_b128 v[160:163], v160 offset:3072
	ds_read_b128 v[164:167], v176
	ds_read_b128 v[168:171], v176 offset:1024
	ds_read_b128 v[172:175], v176 offset:2048
	ds_read_b128 v[176:179], v176 offset:3072
	s_add_u32 s8, s8, 0x40000
	s_addc_u32 s9, s9, 0
	s_mov_b32 m0, s95
	v_lshl_add_u64 v[222:223], s[8:9], 0, v[150:151]
	ds_read_b128 v[182:185], v181 offset:32768
	ds_read_b128 v[186:189], v181 offset:33792
	ds_read_b128 v[190:193], v181 offset:34816
	ds_read_b128 v[194:197], v181 offset:35840
	ds_read_b128 v[198:201], v181 offset:36864
	ds_read_b128 v[202:205], v181 offset:37888
	ds_read_b128 v[206:209], v181 offset:38912
	ds_read_b128 v[210:213], v181 offset:39936
	global_load_lds_dwordx4 v[222:223], off
	v_lshl_add_u64 v[222:223], s[8:9], 0, v[146:147]
	s_mov_b32 m0, s65
	s_nop 0
	global_load_lds_dwordx4 v[222:223], off
	s_waitcnt vmcnt(8)
	s_waitcnt lgkmcnt(0)
	s_barrier
	s_setprio 1
	s_waitcnt lgkmcnt(0)
	v_mfma_f32_16x16x32_bf16 v[126:129], v[130:133], v[182:185], v[126:129]
	v_mfma_f32_16x16x32_bf16 v[122:125], v[156:159], v[182:185], v[122:125]
	v_mfma_f32_16x16x32_bf16 v[118:121], v[130:133], v[190:193], v[118:121]
	v_mfma_f32_16x16x32_bf16 v[114:117], v[156:159], v[190:193], v[114:117]
	v_mfma_f32_16x16x32_bf16 v[110:113], v[130:133], v[198:201], v[110:113]
	v_mfma_f32_16x16x32_bf16 v[106:109], v[156:159], v[198:201], v[106:109]
	v_mfma_f32_16x16x32_bf16 v[102:105], v[130:133], v[206:209], v[102:105]
	v_mfma_f32_16x16x32_bf16 v[98:101], v[156:159], v[206:209], v[98:101]
	v_mfma_f32_16x16x32_bf16 v[126:129], v[134:137], v[186:189], v[126:129]
	v_mfma_f32_16x16x32_bf16 v[122:125], v[160:163], v[186:189], v[122:125]
	v_mfma_f32_16x16x32_bf16 v[118:121], v[134:137], v[194:197], v[118:121]
	v_mfma_f32_16x16x32_bf16 v[114:117], v[160:163], v[194:197], v[114:117]
	v_mfma_f32_16x16x32_bf16 v[110:113], v[134:137], v[202:205], v[110:113]
	v_mfma_f32_16x16x32_bf16 v[106:109], v[160:163], v[202:205], v[106:109]
	v_mfma_f32_16x16x32_bf16 v[102:105], v[134:137], v[210:213], v[102:105]
	v_mfma_f32_16x16x32_bf16 v[98:101], v[160:163], v[210:213], v[98:101]
	s_setprio 0
	s_setprio 1
	v_mfma_f32_16x16x32_bf16 v[62:65], v[164:167], v[182:185], v[62:65]
	v_mfma_f32_16x16x32_bf16 v[58:61], v[172:175], v[182:185], v[58:61]
	v_mfma_f32_16x16x32_bf16 v[54:57], v[164:167], v[190:193], v[54:57]
	v_mfma_f32_16x16x32_bf16 v[50:53], v[172:175], v[190:193], v[50:53]
	v_mfma_f32_16x16x32_bf16 v[46:49], v[164:167], v[198:201], v[46:49]
	v_mfma_f32_16x16x32_bf16 v[42:45], v[172:175], v[198:201], v[42:45]
	v_mfma_f32_16x16x32_bf16 v[38:41], v[164:167], v[206:209], v[38:41]
	v_mfma_f32_16x16x32_bf16 v[34:37], v[172:175], v[206:209], v[34:37]
	v_mfma_f32_16x16x32_bf16 v[62:65], v[168:171], v[186:189], v[62:65]
	v_mfma_f32_16x16x32_bf16 v[58:61], v[176:179], v[186:189], v[58:61]
	v_mfma_f32_16x16x32_bf16 v[54:57], v[168:171], v[194:197], v[54:57]
	v_mfma_f32_16x16x32_bf16 v[50:53], v[176:179], v[194:197], v[50:53]
	v_mfma_f32_16x16x32_bf16 v[46:49], v[168:171], v[202:205], v[46:49]
	v_mfma_f32_16x16x32_bf16 v[42:45], v[176:179], v[202:205], v[42:45]
	v_mfma_f32_16x16x32_bf16 v[38:41], v[168:171], v[210:213], v[38:41]
	v_mfma_f32_16x16x32_bf16 v[34:37], v[176:179], v[210:213], v[34:37]
	s_setprio 0
	s_barrier
	s_add_i32 s8, s19, s51
	v_lshl_add_u64 v[214:215], v[214:215], 0, s[54:55]
	s_mov_b32 m0, s8
	ds_read_b128 v[182:185], v181 offset:49152
	ds_read_b128 v[186:189], v181 offset:50176
	ds_read_b128 v[190:193], v181 offset:51200
	ds_read_b128 v[194:197], v181 offset:52224
	ds_read_b128 v[198:201], v181 offset:53248
	ds_read_b128 v[202:205], v181 offset:54272
	ds_read_b128 v[206:209], v181 offset:55296
	ds_read_b128 v[210:213], v181 offset:56320
	global_load_lds_dwordx4 v[214:215], off
	s_add_i32 m0, s8, 0x2000
	s_add_u32 s6, s6, 0x40080
	v_lshl_add_u64 v[214:215], v[216:217], 0, s[54:55]
	s_addc_u32 s7, s7, 0
	s_add_i32 s8, s20, s51
	global_load_lds_dwordx4 v[214:215], off
	v_lshl_add_u64 v[214:215], s[6:7], 0, v[148:149]
	s_mov_b32 m0, s8
	s_nop 0
	global_load_lds_dwordx4 v[214:215], off
	v_lshl_add_u64 v[214:215], s[6:7], 0, v[144:145]
	s_add_i32 m0, s8, 0x2000
	s_nop 0
	global_load_lds_dwordx4 v[214:215], off
	v_lshl_add_u64 v[214:215], v[218:219], 0, s[54:55]
	s_mov_b32 m0, s60
	s_nop 0
	global_load_lds_dwordx4 v[214:215], off
	v_lshl_add_u64 v[214:215], v[220:221], 0, s[54:55]
	s_mov_b32 m0, s61
	s_nop 0
	global_load_lds_dwordx4 v[214:215], off
	s_waitcnt vmcnt(8)
	s_waitcnt lgkmcnt(0)
	s_barrier
	s_setprio 1
	s_waitcnt lgkmcnt(0)
	v_mfma_f32_16x16x32_bf16 v[94:97], v[130:133], v[182:185], v[94:97]
	v_mfma_f32_16x16x32_bf16 v[90:93], v[156:159], v[182:185], v[90:93]
	v_mfma_f32_16x16x32_bf16 v[86:89], v[130:133], v[190:193], v[86:89]
	v_mfma_f32_16x16x32_bf16 v[82:85], v[156:159], v[190:193], v[82:85]
	v_mfma_f32_16x16x32_bf16 v[78:81], v[130:133], v[198:201], v[78:81]
	v_mfma_f32_16x16x32_bf16 v[74:77], v[156:159], v[198:201], v[74:77]
	v_mfma_f32_16x16x32_bf16 v[70:73], v[130:133], v[206:209], v[70:73]
	v_mfma_f32_16x16x32_bf16 v[66:69], v[156:159], v[206:209], v[66:69]
	v_mfma_f32_16x16x32_bf16 v[94:97], v[134:137], v[186:189], v[94:97]
	v_mfma_f32_16x16x32_bf16 v[90:93], v[160:163], v[186:189], v[90:93]
	v_mfma_f32_16x16x32_bf16 v[86:89], v[134:137], v[194:197], v[86:89]
	v_mfma_f32_16x16x32_bf16 v[82:85], v[160:163], v[194:197], v[82:85]
	v_mfma_f32_16x16x32_bf16 v[78:81], v[134:137], v[202:205], v[78:81]
	v_mfma_f32_16x16x32_bf16 v[74:77], v[160:163], v[202:205], v[74:77]
	v_mfma_f32_16x16x32_bf16 v[70:73], v[134:137], v[210:213], v[70:73]
	v_mfma_f32_16x16x32_bf16 v[66:69], v[160:163], v[210:213], v[66:69]
	s_setprio 0
	s_setprio 1
	v_mfma_f32_16x16x32_bf16 v[30:33], v[164:167], v[182:185], v[30:33]
	v_mfma_f32_16x16x32_bf16 v[26:29], v[172:175], v[182:185], v[26:29]
	v_mfma_f32_16x16x32_bf16 v[22:25], v[164:167], v[190:193], v[22:25]
	v_mfma_f32_16x16x32_bf16 v[18:21], v[172:175], v[190:193], v[18:21]
	v_mfma_f32_16x16x32_bf16 v[14:17], v[164:167], v[198:201], v[14:17]
	v_mfma_f32_16x16x32_bf16 v[10:13], v[172:175], v[198:201], v[10:13]
	v_mfma_f32_16x16x32_bf16 v[6:9], v[164:167], v[206:209], v[6:9]
	v_mfma_f32_16x16x32_bf16 v[0:3], v[172:175], v[206:209], v[0:3]
	v_mfma_f32_16x16x32_bf16 v[30:33], v[168:171], v[186:189], v[30:33]
	v_mfma_f32_16x16x32_bf16 v[26:29], v[176:179], v[186:189], v[26:29]
	v_mfma_f32_16x16x32_bf16 v[22:25], v[168:171], v[194:197], v[22:25]
	v_mfma_f32_16x16x32_bf16 v[18:21], v[176:179], v[194:197], v[18:21]
	v_mfma_f32_16x16x32_bf16 v[14:17], v[168:171], v[202:205], v[14:17]
	v_mfma_f32_16x16x32_bf16 v[10:13], v[176:179], v[202:205], v[10:13]
	v_mfma_f32_16x16x32_bf16 v[6:9], v[168:171], v[210:213], v[6:9]
	v_mfma_f32_16x16x32_bf16 v[0:3], v[176:179], v[210:213], v[0:3]
	s_setprio 0
	s_add_u32 s0, s0, 0x100
	s_addc_u32 s1, s1, 0
	s_add_u32 s16, s16, 0x100
	s_addc_u32 s17, s17, 0
	s_cmp_ge_i32 s18, s90
	s_mov_b32 s6, s18
	s_cbranch_scc1 .Lrotx_4
	s_add_i32 s18, s6, 2
	s_add_u32 s7, s0, 0xfffc0080
	s_addc_u32 s8, s1, -1
	s_add_i32 s19, 32, 0x10000
	s_cmp_eq_u32 s56, s6
	s_cselect_b32 s9, s12, s8
	s_cselect_b32 s8, s13, s7
	s_cselect_b32 s7, s14, s17
	s_cselect_b32 s6, s15, s16
	s_add_i32 s22, 32, 0x14000
	s_barrier
	s_branch .Lrot_4
.Lrotx_4:
	s_barrier
.LBB0_1509:
	s_and_b64 vcc, exec, s[76:77]
	s_cbranch_vccz .LBB0_1511
	s_barrier
